# hand-written up-proj epilogue for prompt AND sample tiles; conv weights staged in LDS by LDS-DMA one unit ahead (no vmcnt drain in the epilogue)
# speedup vs baseline: 1.0514x; 1.0348x over previous
; template <class Epi, class Sched, bool ALIGN_EPI = false, bool SP2 = false>
; __device__ __forceinline__ void gemm_phase(PG8_LAS unsigned char* lds, const Gemm g, const Sched& S, const Epi& E) {
;     const int tid = threadIdx.x, wid = __builtin_amdgcn_readfirstlane(tid >> 6), lane = tid & 63, wr = wid >> 2, wc = wid & 3, fr = lane & 15, fq = lane >> 4;
;     const int K = g.K, nt = K / BK;
;     unsigned voffA[2], voffB[2];
; #pragma unroll
;     for (int i = 0; i < 2; ++i) { int R, C; stage_rc(tid * 16 + i * 8192, R, C); const int Rb = Epi::PERM ? ((R & ~31) + perm32(R & 31)) : R;
;         voffA[i] = (unsigned)(R * K + C) * 2u; voffB[i] = (unsigned)(Rb * K + C) * 2u; }
;     const size_t kstep = (size_t)(BK * 2);
;     const size_t hstep = (size_t)HALF * K * 2;
;     const size_t tstep = 2 * hstep;
;     const unsigned ldsw = (unsigned)wid * 1024u;
;     const int aoff = lds_byte(wr * 64 + fr, fq * 8), boff = lds_byte(wc * 32 + fr, fq * 8);
;     ...
;     Unit cur, nxt; int ui = 0;
;     if (!S.next(0, cur)) return;
;     f32x4 acc[2][2][4][2];
; #pragma unroll
;     for (int a = 0; a < 2; ++a)
; #pragma unroll
;         for (int b = 0; b < 2; ++b)
; #pragma unroll
;             for (int m = 0; m < 4; ++m)
; #pragma unroll
;                 for (int n = 0; n < 2; ++n) acc[a][b][m][n] = (f32x4){0.f, 0.f, 0.f, 0.f};
;     bf16x8 At[4][2], B0[2][2], B1[2][2];
;     const char* cA = (const char*)g.A + (size_t)cur.pm * tstep; const char* cB = (const char*)g.Bt + (size_t)cur.pn * tstep;
;     S.a_ready(cur);
;     if constexpr (SP2) {
;         PG8_STAGE(PG8_SB(0, 0), cB, voffB); PG8_STAGE(PG8_SB(0, 1), cB + hstep, voffB); PG8_STAGE(PG8_SA(0, 0), cA, voffA); PG8_STAGE(PG8_SA(0, 1), cA + hstep, voffA);
;         if (wr == 1) PG8_BAR;
;         PG8_WAIT_V(2); PG8_BAR;
;         PG8_STAGE(PG8_SB(1, 0), cB + kstep, voffB); PG8_STAGE(PG8_SA(1, 0), cA + kstep, voffA); PG8_STAGE(PG8_SB(1, 1), cB + hstep + kstep, voffB);
;         PG8_WAIT_V(6); PG8_BAR;
;     } else {
;         PG8_STAGE(PG8_SB(0, 0), cB, voffB); PG8_STAGE(PG8_SA(0, 0), cA, voffA); PG8_STAGE(PG8_SB(0, 1), cB + hstep, voffB); PG8_STAGE(PG8_SA(0, 1), cA + hstep, voffA);
;         if (wr == 1) PG8_BAR;
;         PG8_WAIT_V(4); PG8_BAR;
;         PG8_STAGE(PG8_SB(1, 0), cB + kstep, voffB); PG8_STAGE(PG8_SA(1, 0), cA + kstep, voffA); PG8_STAGE(PG8_SB(1, 1), cB + hstep + kstep, voffB);
.LBB0_879:
	v_readlane_b32 s52, v254, 44
	v_readlane_b32 s54, v254, 46
	v_readlane_b32 s55, v254, 47
	v_readlane_b32 s56, v254, 48
	v_readlane_b32 s57, v254, 49
	v_readlane_b32 s58, v254, 50
	v_readlane_b32 s59, v254, 51
	v_readlane_b32 s60, v254, 52
	v_readlane_b32 s61, v254, 53
	v_readlane_b32 s62, v254, 54
	v_readlane_b32 s63, v254, 55
	s_and_b32 s9, s0, 3
	v_readlane_b32 s64, v254, 56
	v_readlane_b32 s65, v254, 57
	v_readlane_b32 s66, v254, 58
	v_readlane_b32 s67, v254, 59
	s_mov_b64 s[54:55], s[58:59]
	s_mov_b64 s[56:57], s[60:61]
	v_and_b32_e32 v172, 15, v0
	v_bfe_u32 v14, v0, 4, 2
	s_lshl_b32 s0, s3, 13
	s_lshl_b32 s4, s9, 12
	s_mov_b64 s[58:59], s[62:63]
	s_mov_b64 s[60:61], s[64:65]
	s_mov_b64 s[62:63], s[66:67]
	v_lshlrev_b32_e32 v16, 4, v14
	v_lshlrev_b32_e32 v18, 2, v172
	s_add_u32 s20, s62, 0x6c2a000
	s_mov_b64 s[22:23], 0x80
	v_lshl_or_b32 v17, v172, 6, v16
	v_and_b32_e32 v19, 32, v18
	s_addc_u32 s21, s63, 0
	s_add_i32 m0, s45, 0x18000
	v_lshl_add_u64 v[8:9], v[8:9], 0, s[22:23]
	v_bitop3_b32 v17, v17, s0, v19 bitop3:0xde
	v_lshlrev_b32_e32 v19, 6, v0
	s_movk_i32 s0, 0x3c0
	s_waitcnt vmcnt(2)
	s_barrier
	global_load_lds_dwordx4 v[8:9], off
	v_lshl_add_u64 v[6:7], v[6:7], 0, s[22:23]
	s_add_i32 m0, s45, 0x1a000
	s_add_i32 s49, s45, 0x8000
	s_add_i32 s50, s45, 0xa000
	v_and_or_b32 v16, v19, s0, v16
	global_load_lds_dwordx4 v[6:7], off
	v_lshl_add_u64 v[4:5], v[4:5], 0, s[22:23]
	s_mov_b32 m0, s49
	s_add_u32 s0, s34, 0x40080
	global_load_lds_dwordx4 v[4:5], off
	v_lshl_add_u64 v[2:3], v[2:3], 0, s[22:23]
	s_mov_b32 m0, s50
	s_addc_u32 s1, s35, 0
	global_load_lds_dwordx4 v[2:3], off
	s_add_i32 m0, s45, 0x1c000
	v_lshl_add_u64 v[2:3], s[0:1], 0, v[166:167]
	global_load_lds_dwordx4 v[2:3], off
	v_lshl_add_u64 v[2:3], s[0:1], 0, v[170:171]
	s_add_i32 m0, s45, 0x1e000
	s_cmpk_lt_u32 s2, 0x100
	global_load_lds_dwordx4 v[2:3], off
	v_lshlrev_b32_e32 v19, 2, v0
	s_cselect_b64 s[24:25], -1, 0
	v_add_u32_e32 v174, -14, v172
	s_lshl_b32 s0, s3, 5
	s_lshl_b32 s1, s9, 3
	v_and_b32_e32 v19, 32, v19
	v_lshl_add_u32 v2, v14, 1, v174
	s_or_b32 s0, s1, s0
	v_and_b32_e32 v3, 7, v0
	s_xor_b64 s[38:39], s[12:13], -1
	v_bitop3_b32 v203, s4, v16, v19 bitop3:0xf6
	v_add_lshl_u32 v215, s0, v2, 5
	v_cmp_gt_u32_e64 s[0:1], 2, v3
	v_cmp_eq_u32_e64 s[4:5], 0, v3
	v_cmp_lt_u32_e64 s[30:31], 5, v3
	v_add_u32_e32 v176, -6, v3
	v_cndmask_b32_e64 v3, 0, 1, s[38:39]
	v_or_b32_e32 v3, s8, v3
	s_lshl_b32 s2, s9, 2
	v_lshlrev_b32_e32 v3, 4, v3
	v_or_b32_e32 v5, s2, v14
	v_or_b32_e32 v3, s2, v3
	s_lshl_b32 s2, s3, 8
	v_cmp_lt_u32_e64 s[26:27], 13, v172
	v_cmp_gt_u32_e32 vcc, 2, v172
	s_add_i32 s2, s2, 0
	s_and_b64 s[38:39], s[24:25], vcc
	s_and_b64 s[40:41], s[12:13], s[26:27]
	s_add_i32 s2, s2, 0x22000
	v_readlane_b32 s53, v254, 45
	s_add_u32 s52, s54, 0x2c00
	s_addc_u32 s53, s55, 0
	v_or_b32_e32 v3, v3, v14
	s_add_u32 s54, s54, 0x5800
	v_lshlrev_b32_e32 v4, 5, v172
	v_lshlrev_b32_e32 v3, 6, v3
	s_addc_u32 s55, s55, 0
	s_add_i32 s51, 0, 0x21000
	v_add3_u32 v3, s51, v3, v4
	v_lshlrev_b32_e32 v5, 6, v5
	v_add_u32_e32 v218, 0xfffffe40, v3
	v_add_u32_e32 v220, 0xfffffe50, v3
	v_lshlrev_b32_e32 v3, 8, v0
	v_add3_u32 v5, s51, v5, v4
	v_and_b32_e32 v3, 0x18000, v3
	v_lshlrev_b32_e32 v4, 11, v12
	v_or3_b32 v3, v10, v3, v4
	v_add_u32_e32 v180, v3, v11
	v_lshlrev_b32_e32 v3, 4, v13
	s_waitcnt vmcnt(6)
	v_and_b32_e32 v3, 0x38000, v3
	v_lshlrev_b32_e32 v15, 3, v14
	v_add_u32_e32 v2, 0x800, v215
	v_or3_b32 v3, v10, v3, v4
	s_add_i32 s57, 0, 0x10000
	s_add_i32 s59, 0, 0x14000
	v_lshl_or_b32 v173, s3, 6, v172
	v_lshl_or_b32 v214, s9, 5, v15
	v_mov_b32_e32 v177, v167
	v_cmp_eq_u32_e64 s[6:7], 15, v172
	v_mov_b32_e32 v175, v167
	v_add_u32_e32 v178, -12, v172
	v_mov_b32_e32 v179, v167
	v_add_u32_e32 v216, s2, v18
	v_add_u32_e32 v217, 0xfffffe40, v5
	v_add_u32_e32 v219, 0xfffffe50, v5
	v_mov_b32_e32 v181, v167
	v_add_u32_e32 v182, v3, v11
	v_mov_b32_e32 v183, v167
	v_mov_b64_e32 v[184:185], 0x5d8
	v_mov_b64_e32 v[186:187], 0x5d7
	v_add_u32_e32 v221, s57, v203
	v_add_u32_e32 v222, s59, v203
	v_add_u32_e32 v223, 0, v17
	s_movk_i32 s62, 0x5800
	s_movk_i32 s63, 0x2c00
	s_mov_b32 s56, 0xc0135761
	s_mov_b32 s58, 0xbdd2d3e8
	s_movk_i32 s76, 0x1600
	v_add_u32_e32 v224, s51, v2
	v_mov_b32_e32 v225, 0x2c00
	s_mov_b32 s77, 0
	s_barrier
	v_readfirstlane_b32 s80, v0
	v_readlane_b32 s82, v254, 50
	v_readlane_b32 s83, v254, 51
	v_readlane_b32 s84, v254, 52
	v_readlane_b32 s85, v254, 53
	v_and_b32_e32 v86, 31, v202
	v_lshlrev_b32_e32 v86, 4, v86
	s_lshr_b32 s80, s80, 6
	s_cmp_lg_u32 s80, 0
	s_cbranch_scc1 .Le5dma0_skip
	s_lshl_b32 s81, s10, 9
	v_add_u32_e32 v86, s81, v86
	v_mov_b32_e32 v87, 0
	v_cmp_lt_u32_e64 s[86:87], 31, v202
	v_mov_b32_e32 v92, s84
	v_mov_b32_e32 v93, s85
	v_mov_b32_e32 v98, s82
	v_mov_b32_e32 v99, s83
	s_and_b32 s81, s11, 1
	s_lshl_b32 s81, s81, 11
	s_add_i32 s81, s81, 0x24000
	v_cndmask_b32_e64 v92, v92, v98, s[86:87]
	v_cndmask_b32_e64 v93, v93, v99, s[86:87]
	v_lshl_add_u64 v[92:93], v[92:93], 0, v[86:87]
	s_mov_b32 m0, s81
	s_nop 0
	global_load_lds_dwordx4 v[92:93], off
	v_mov_b32_e32 v92, 0x2c00
	v_mov_b32_e32 v93, 0x5800
	s_nop 0
	v_cndmask_b32_e64 v92, v92, v93, s[86:87]
	v_add_u32_e32 v86, v86, v92
	v_lshl_add_u64 v[98:99], v[98:99], 0, v[86:87]
	s_add_i32 m0, s81, 0x400
	s_nop 0
	global_load_lds_dwordx4 v[98:99], off
.Le5dma0_skip:
	s_branch .LBB0_882
.LBB0_880:
	s_mov_b64 s[2:3], 0

; #define PG8_LAS __attribute__((address_space(3)))
;     __device__ __forceinline__ void operator()(const f32x4 (&acc)[2][2][4][2], const Unit& u, int wr, int wc, int fr, int fq) const {
;         const int lane = fq * 16 + fr, row0 = u.pm * BM + wr * 64 + fr, j0 = u.pn * 128 + wc * 32 + 8 * fq;
;         const bool smp = u.pm >= 64;
;     ...
;         const unsigned long long pu_t0 = __builtin_amdgcn_s_memrealtime();
;     ...
;         float rstd[2][4];
; #pragma unroll
;         for (int ai = 0; ai < 2; ++ai)
; #pragma unroll
;             for (int m = 0; m < 4; ++m) rstd[ai][m] = RSTD[u.idx * 256 + ai * HALF + wr * 64 + m * 16 + fr];
;         if (!smp) {
;             if (fr >= 14) {
; #pragma unroll
;                 for (int ai = 0; ai < 2; ++ai)
; #pragma unroll
;                     for (int n = 0; n < 2; ++n) *(PG8_LAS f32x4*)(xch + ((((ai * 2 + wr) * 4 + wc) * 4 + fq) * 2 + (fr - 14)) * 8 + 4 * n) = acc[ai][0][3][n] * rstd[ai][3]; }
;             asm volatile("s_waitcnt lgkmcnt(0)" ::: "memory"); __builtin_amdgcn_s_barrier(); asm volatile("" ::: "memory");
;         }
;     ...
;         asm volatile("s_waitcnt vmcnt(0)" ::: "memory");
;         if (blockIdx.x == 0 && threadIdx.x == 0) ((volatile PG8_LAS unsigned long long*)((PG8_LAS unsigned char*)xch - 4096 + 512))[43] += __builtin_amdgcn_s_memrealtime() - pu_t0;
;     ...
;         auto ror1 = [](float v) -> float { return __builtin_bit_cast(float, __builtin_amdgcn_mov_dpp(__builtin_bit_cast(int, v), 0x121, 0xf, 0xf, true)); };
;         auto ror2 = [](float v) -> float { return __builtin_bit_cast(float, __builtin_amdgcn_mov_dpp(__builtin_bit_cast(int, v), 0x122, 0xf, 0xf, true)); };
;         u32x2 pk0[2][4];
; #pragma unroll
;         for (int n = 0; n < 2; ++n) {
;             const f32x4 cb = *(const f32x4*)(conv_b + j0 + 4 * n), w0 = *(const f32x4*)(conv_w + j0 + 4 * n), w1 = *(const f32x4*)(conv_w + FF + j0 + 4 * n), w2 = *(const f32x4*)(conv_w + 2 * FF + j0 + 4 * n);
.LBB0_888:
	s_and_b64 vcc, exec, s[8:9]
	s_cbranch_vccz .Le5dma1_skip
	v_readfirstlane_b32 s80, v0
	v_readlane_b32 s82, v254, 50
	v_readlane_b32 s83, v254, 51
	v_readlane_b32 s84, v254, 52
	v_readlane_b32 s85, v254, 53
	v_and_b32_e32 v86, 31, v202
	v_lshlrev_b32_e32 v86, 4, v86
	s_lshr_b32 s80, s80, 6
	s_cmp_lg_u32 s80, 0
	s_cbranch_scc1 .Le5dma1_skip
	s_lshl_b32 s81, s60, 9
	v_add_u32_e32 v86, s81, v86
	v_mov_b32_e32 v87, 0
	v_cmp_lt_u32_e64 s[86:87], 31, v202
	v_mov_b32_e32 v92, s84
	v_mov_b32_e32 v93, s85
	v_mov_b32_e32 v98, s82
	v_mov_b32_e32 v99, s83
	s_and_b32 s81, s78, 1
	s_lshl_b32 s81, s81, 11
	s_add_i32 s81, s81, 0x24000
	v_cndmask_b32_e64 v92, v92, v98, s[86:87]
	v_cndmask_b32_e64 v93, v93, v99, s[86:87]
	v_lshl_add_u64 v[92:93], v[92:93], 0, v[86:87]
	s_mov_b32 m0, s81
	s_nop 0
	global_load_lds_dwordx4 v[92:93], off
	v_mov_b32_e32 v92, 0x2c00
	v_mov_b32_e32 v93, 0x5800
	s_nop 0
	v_cndmask_b32_e64 v92, v92, v93, s[86:87]
	v_add_u32_e32 v86, v86, v92
	v_lshl_add_u64 v[98:99], v[98:99], 0, v[86:87]
	s_add_i32 m0, s81, 0x400
	s_nop 0
	global_load_lds_dwordx4 v[98:99], off
.Le5dma1_skip:
	s_cmp_gt_i32 s28, 63
	s_cbranch_scc0 .Lepi5_hand
	s_branch .Lepi5_smp
; #define PG8_LAS __attribute__((address_space(3)))
;     __device__ __forceinline__ void operator()(const f32x4 (&acc)[2][2][4][2], const Unit& u, int wr, int wc, int fr, int fq) const {
;     ...
;         float rstd[2][4];
; #pragma unroll
;         for (int ai = 0; ai < 2; ++ai)
; #pragma unroll
;             for (int m = 0; m < 4; ++m) rstd[ai][m] = RSTD[u.idx * 256 + ai * HALF + wr * 64 + m * 16 + fr];
;         if (!smp) {
;             if (fr >= 14) {
; #pragma unroll
;                 for (int ai = 0; ai < 2; ++ai)
; #pragma unroll
;                     for (int n = 0; n < 2; ++n) *(PG8_LAS f32x4*)(xch + ((((ai * 2 + wr) * 4 + wc) * 4 + fq) * 2 + (fr - 14)) * 8 + 4 * n) = acc[ai][0][3][n] * rstd[ai][3]; }
;             asm volatile("s_waitcnt lgkmcnt(0)" ::: "memory"); __builtin_amdgcn_s_barrier(); asm volatile("" ::: "memory");
;         }
;     ...
;         asm volatile("s_waitcnt vmcnt(0)" ::: "memory");
;         if (blockIdx.x == 0 && threadIdx.x == 0) ((volatile PG8_LAS unsigned long long*)((PG8_LAS unsigned char*)xch - 4096 + 512))[43] += __builtin_amdgcn_s_memrealtime() - pu_t0;
;     ...
;         auto ror1 = [](float v) -> float { return __builtin_bit_cast(float, __builtin_amdgcn_mov_dpp(__builtin_bit_cast(int, v), 0x121, 0xf, 0xf, true)); };
;         auto ror2 = [](float v) -> float { return __builtin_bit_cast(float, __builtin_amdgcn_mov_dpp(__builtin_bit_cast(int, v), 0x122, 0xf, 0xf, true)); };
;         u32x2 pk0[2][4];
; #pragma unroll
;         for (int n = 0; n < 2; ++n) {
;             const f32x4 cb = *(const f32x4*)(conv_b + j0 + 4 * n), w0 = *(const f32x4*)(conv_w + j0 + 4 * n), w1 = *(const f32x4*)(conv_w + FF + j0 + 4 * n), w2 = *(const f32x4*)(conv_w + 2 * FF + j0 + 4 * n);
; #pragma unroll
;             for (int ai = 0; ai < 2; ++ai) {
;                 f32x4 pa = (f32x4){0.f, 0.f, 0.f, 0.f};
;                 if (!smp && fr >= 14 && (wr == 1 || ai == 1)) { const int sai = wr == 1 ? ai : 0, swr = wr == 1 ? 0 : 1;
;                     pa = *(const PG8_LAS f32x4*)(xch + ((((sai * 2 + swr) * 4 + wc) * 4 + fq) * 2 + (fr - 14)) * 8 + 4 * n); }
.Lepi5_hand:
	v_readfirstlane_b32 s70, v0
	v_readlane_b32 s86, v254, 19
	v_readlane_b32 s87, v254, 20
	v_and_b32_e32 v200, 15, v202
	v_lshrrev_b32_e32 v201, 4, v202
	s_nop 1
	v_cmp_lt_u32_e64 s[90:91], 13, v200
	v_cmp_gt_u32_e64 s[92:93], 2, v200
	v_cmp_eq_u32_e64 s[94:95], 0, v200
	s_lshr_b32 s70, s70, 6
	s_lshr_b32 s71, s70, 2
	s_and_b32 s72, s70, 3
	s_sub_u32 s86, s86, 0x4000
	s_subb_u32 s87, s87, 0
	s_lshl_b32 s73, s10, 7
	s_lshl_b32 s74, s72, 5
	s_add_i32 s73, s73, s74
	v_lshl_add_u32 v213, v201, 3, s73
	v_lshlrev_b32_e32 v213, 2, v213
	s_lshl_b32 s73, s11, 10
	s_lshl_b32 s74, s71, 8
	s_add_i32 s73, s73, s74
	s_add_i32 s73, s73, 0x22000
	v_lshl_add_u32 v99, v200, 2, s73
	ds_read2_b32 v[152:153], v99 offset1:16
	ds_read2_b32 v[154:155], v99 offset0:32 offset1:48
	ds_read2_b32 v[156:157], v99 offset0:128 offset1:144
	ds_read2_b32 v[158:159], v99 offset0:160 offset1:176
	s_mul_i32 s74, s71, 0x58000
	v_lshrrev_b32_e32 v212, 1, v213
	v_add_u32_e32 v212, s74, v212
	s_movk_i32 s75, 0x1600
	v_mad_u32_u24 v212, v200, s75, v212
	s_waitcnt lgkmcnt(0)
	v_pk_mul_f32 v[148:149], v[148:149], v[152:153] op_sel_hi:[1,0]
	v_pk_mul_f32 v[150:151], v[150:151], v[152:153] op_sel_hi:[1,0]
	v_pk_mul_f32 v[62:63], v[62:63], v[152:153] op_sel_hi:[1,0]
	v_pk_mul_f32 v[64:65], v[64:65], v[152:153] op_sel_hi:[1,0]
	v_pk_mul_f32 v[144:145], v[144:145], v[152:153] op_sel_hi:[1,0]
	v_pk_mul_f32 v[146:147], v[146:147], v[152:153] op_sel_hi:[1,0]
	v_pk_mul_f32 v[58:59], v[58:59], v[152:153] op_sel_hi:[1,0]
	v_pk_mul_f32 v[60:61], v[60:61], v[152:153] op_sel_hi:[1,0]
	v_pk_mul_f32 v[140:141], v[140:141], v[152:153] op_sel:[0,1] op_sel_hi:[1,1]
	v_pk_mul_f32 v[142:143], v[142:143], v[152:153] op_sel:[0,1] op_sel_hi:[1,1]
	v_pk_mul_f32 v[54:55], v[54:55], v[152:153] op_sel:[0,1] op_sel_hi:[1,1]
	v_pk_mul_f32 v[56:57], v[56:57], v[152:153] op_sel:[0,1] op_sel_hi:[1,1]
	v_pk_mul_f32 v[136:137], v[136:137], v[152:153] op_sel:[0,1] op_sel_hi:[1,1]
	v_pk_mul_f32 v[138:139], v[138:139], v[152:153] op_sel:[0,1] op_sel_hi:[1,1]
	v_pk_mul_f32 v[50:51], v[50:51], v[152:153] op_sel:[0,1] op_sel_hi:[1,1]
	v_pk_mul_f32 v[52:53], v[52:53], v[152:153] op_sel:[0,1] op_sel_hi:[1,1]
	v_pk_mul_f32 v[132:133], v[132:133], v[154:155] op_sel_hi:[1,0]
	v_pk_mul_f32 v[134:135], v[134:135], v[154:155] op_sel_hi:[1,0]
	v_pk_mul_f32 v[46:47], v[46:47], v[154:155] op_sel_hi:[1,0]
	v_pk_mul_f32 v[48:49], v[48:49], v[154:155] op_sel_hi:[1,0]
	v_pk_mul_f32 v[128:129], v[128:129], v[154:155] op_sel_hi:[1,0]
	v_pk_mul_f32 v[130:131], v[130:131], v[154:155] op_sel_hi:[1,0]
	v_pk_mul_f32 v[42:43], v[42:43], v[154:155] op_sel_hi:[1,0]
	v_pk_mul_f32 v[44:45], v[44:45], v[154:155] op_sel_hi:[1,0]
	v_pk_mul_f32 v[124:125], v[124:125], v[154:155] op_sel:[0,1] op_sel_hi:[1,1]
	v_pk_mul_f32 v[126:127], v[126:127], v[154:155] op_sel:[0,1] op_sel_hi:[1,1]
	v_pk_mul_f32 v[38:39], v[38:39], v[154:155] op_sel:[0,1] op_sel_hi:[1,1]
	v_pk_mul_f32 v[40:41], v[40:41], v[154:155] op_sel:[0,1] op_sel_hi:[1,1]
	v_pk_mul_f32 v[94:95], v[94:95], v[154:155] op_sel:[0,1] op_sel_hi:[1,1]
	v_pk_mul_f32 v[96:97], v[96:97], v[154:155] op_sel:[0,1] op_sel_hi:[1,1]
	v_pk_mul_f32 v[34:35], v[34:35], v[154:155] op_sel:[0,1] op_sel_hi:[1,1]
	v_pk_mul_f32 v[36:37], v[36:37], v[154:155] op_sel:[0,1] op_sel_hi:[1,1]
	v_pk_mul_f32 v[120:121], v[120:121], v[156:157] op_sel_hi:[1,0]
	v_pk_mul_f32 v[122:123], v[122:123], v[156:157] op_sel_hi:[1,0]
	v_pk_mul_f32 v[30:31], v[30:31], v[156:157] op_sel_hi:[1,0]
	v_pk_mul_f32 v[32:33], v[32:33], v[156:157] op_sel_hi:[1,0]
	v_pk_mul_f32 v[100:101], v[100:101], v[156:157] op_sel_hi:[1,0]
	v_pk_mul_f32 v[102:103], v[102:103], v[156:157] op_sel_hi:[1,0]
	v_pk_mul_f32 v[26:27], v[26:27], v[156:157] op_sel_hi:[1,0]
	v_pk_mul_f32 v[28:29], v[28:29], v[156:157] op_sel_hi:[1,0]
	v_pk_mul_f32 v[88:89], v[88:89], v[156:157] op_sel:[0,1] op_sel_hi:[1,1]
	v_pk_mul_f32 v[90:91], v[90:91], v[156:157] op_sel:[0,1] op_sel_hi:[1,1]
	v_pk_mul_f32 v[22:23], v[22:23], v[156:157] op_sel:[0,1] op_sel_hi:[1,1]
	v_pk_mul_f32 v[24:25], v[24:25], v[156:157] op_sel:[0,1] op_sel_hi:[1,1]
	v_pk_mul_f32 v[82:83], v[82:83], v[156:157] op_sel:[0,1] op_sel_hi:[1,1]
	v_pk_mul_f32 v[84:85], v[84:85], v[156:157] op_sel:[0,1] op_sel_hi:[1,1]
	v_pk_mul_f32 v[18:19], v[18:19], v[156:157] op_sel:[0,1] op_sel_hi:[1,1]
	v_pk_mul_f32 v[20:21], v[20:21], v[156:157] op_sel:[0,1] op_sel_hi:[1,1]
	v_pk_mul_f32 v[78:79], v[78:79], v[158:159] op_sel_hi:[1,0]
	v_pk_mul_f32 v[80:81], v[80:81], v[158:159] op_sel_hi:[1,0]
	v_pk_mul_f32 v[14:15], v[14:15], v[158:159] op_sel_hi:[1,0]
	v_pk_mul_f32 v[16:17], v[16:17], v[158:159] op_sel_hi:[1,0]
	v_pk_mul_f32 v[70:71], v[70:71], v[158:159] op_sel_hi:[1,0]
	v_pk_mul_f32 v[72:73], v[72:73], v[158:159] op_sel_hi:[1,0]
	v_pk_mul_f32 v[10:11], v[10:11], v[158:159] op_sel_hi:[1,0]
	v_pk_mul_f32 v[12:13], v[12:13], v[158:159] op_sel_hi:[1,0]
	v_pk_mul_f32 v[74:75], v[74:75], v[158:159] op_sel:[0,1] op_sel_hi:[1,1]
	v_pk_mul_f32 v[76:77], v[76:77], v[158:159] op_sel:[0,1] op_sel_hi:[1,1]
	v_pk_mul_f32 v[6:7], v[6:7], v[158:159] op_sel:[0,1] op_sel_hi:[1,1]
	v_pk_mul_f32 v[8:9], v[8:9], v[158:159] op_sel:[0,1] op_sel_hi:[1,1]
	v_pk_mul_f32 v[66:67], v[66:67], v[158:159] op_sel:[0,1] op_sel_hi:[1,1]
	v_pk_mul_f32 v[68:69], v[68:69], v[158:159] op_sel:[0,1] op_sel_hi:[1,1]
	v_pk_mul_f32 v[2:3], v[2:3], v[158:159] op_sel:[0,1] op_sel_hi:[1,1]
	v_pk_mul_f32 v[4:5], v[4:5], v[158:159] op_sel:[0,1] op_sel_hi:[1,1]
	s_lshl_b32 s73, s70, 8
	s_add_i32 s73, s73, 0x20e40
	v_lshlrev_b32_e32 v99, 6, v201
	v_lshl_add_u32 v99, v200, 5, v99
	v_mov_b32_e32 v188, 0
	v_mov_b32_e32 v189, 0
	v_mov_b32_e32 v190, 0
	v_mov_b32_e32 v191, 0
	v_mov_b32_e32 v192, 0
	v_mov_b32_e32 v193, 0
	v_mov_b32_e32 v194, 0
	v_mov_b32_e32 v195, 0
	v_mov_b32_e32 v196, 0
	v_mov_b32_e32 v197, 0
	v_mov_b32_e32 v198, 0
	v_mov_b32_e32 v199, 0
	v_mov_b32_e32 v160, 0
	v_mov_b32_e32 v161, 0
	v_mov_b32_e32 v162, 0
	v_mov_b32_e32 v163, 0
	v_add_u32_e32 v86, s73, v99
	s_mov_b64 exec, s[90:91]
	ds_write_b128 v86, v[124:127]
	ds_write_b128 v86, v[38:41] offset:16
	ds_write_b128 v86, v[74:77] offset:2048
	ds_write_b128 v86, v[6:9] offset:2064
	s_mov_b64 exec, -1
	s_waitcnt lgkmcnt(0)
	s_barrier
	s_lshl_b32 s73, s72, 8
	s_add_i32 s73, s73, 0x20e40
	v_add_u32_e32 v86, s73, v99
	s_mov_b64 exec, s[90:91]
	s_cmp_eq_u32 s71, 0
	s_cbranch_scc1 .Lepi5_pa_wr0
	ds_read_b128 v[188:191], v86
	ds_read_b128 v[192:195], v86 offset:16
	ds_read_b128 v[196:199], v86 offset:2048
	ds_read_b128 v[160:163], v86 offset:2064
	s_branch .Lepi5_pa_done

; #define PG8_LAS __attribute__((address_space(3)))
;     __device__ __forceinline__ void operator()(const f32x4 (&acc)[2][2][4][2], const Unit& u, int wr, int wc, int fr, int fq) const {
;     ...
;             const f32x4 cb = *(const f32x4*)(conv_b + j0 + 4 * n), w0 = *(const f32x4*)(conv_w + j0 + 4 * n), w1 = *(const f32x4*)(conv_w + FF + j0 + 4 * n), w2 = *(const f32x4*)(conv_w + 2 * FF + j0 + 4 * n);
; #pragma unroll
;             for (int ai = 0; ai < 2; ++ai) {
;                 f32x4 pa = (f32x4){0.f, 0.f, 0.f, 0.f};
;                 if (!smp && fr >= 14 && (wr == 1 || ai == 1)) { const int sai = wr == 1 ? ai : 0, swr = wr == 1 ? 0 : 1;
;                     pa = *(const PG8_LAS f32x4*)(xch + ((((sai * 2 + swr) * 4 + wc) * 4 + fq) * 2 + (fr - 14)) * 8 + 4 * n); }
; #pragma unroll
;                 for (int m = 0; m < 4; ++m) {
;                     const int r = row0 + ai * HALF + m * 16; const float rs = rstd[ai][m];
;                     const f32x4 a = acc[ai][0][m][n] * rs, b = acc[ai][1][m][n] * rs; f32x4 p1, p2;
;                     if (!smp) {
; #pragma unroll
;                         for (int e2 = 0; e2 < 4; ++e2) { const float s1 = fr == 15 ? pa[e2] : a[e2], s2 = fr >= 14 ? pa[e2] : a[e2]; p1[e2] = ror1(s1); p2[e2] = ror2(s2); }
;                         if (ai == 0 && wr == 0 && m == 0 && fr < 2) { *(f32x4*)(EA + ((size_t)u.pm * 4 + fr) * FF + j0 + 4 * n) = a; *(f32x4*)(EB + ((size_t)u.pm * 2 + fr) * FF + j0 + 4 * n) = b; }
;                         if (ai == 1 && wr == 1 && m == 3 && fr >= 14) { *(f32x4*)(EA + ((size_t)u.pm * 4 + 2 + (fr - 14)) * FF + j0 + 4 * n) = a;
;                             if ((u.pm & 7) == 7) *(f32x4*)(o_conv_p + ((size_t)(u.pm >> 3) * 2 + (fr - 14)) * FF + j0 + 4 * n) = a; }
.Lepi5_pa_done:
	s_mov_b64 exec, -1
	s_and_b32 s73, s11, 1
	s_lshl_b32 s73, s73, 11
	s_add_i32 s73, s73, 0x24000
	s_lshl_b32 s74, s72, 7
	s_add_i32 s73, s73, s74
	v_lshl_add_u32 v87, v201, 5, s73
	ds_read_b128 v[226:229], v87 offset:0
	ds_read_b128 v[230:233], v87 offset:16
	ds_read_b128 v[234:237], v87 offset:512
	ds_read_b128 v[238:241], v87 offset:528
	ds_read_b128 v[242:245], v87 offset:1024
	ds_read_b128 v[246:249], v87 offset:1040
	ds_read_b128 v[250:253], v87 offset:1536
	ds_read_b128 v[204:207], v87 offset:1552
	s_waitcnt lgkmcnt(0)
	v_cndmask_b32_e64 v104, 0, v242, s[94:95]
	v_cndmask_b32_e64 v112, 0, v234, s[92:93]
	v_cndmask_b32_e64 v105, 0, v243, s[94:95]
	v_cndmask_b32_e64 v113, 0, v235, s[92:93]
	v_cndmask_b32_e64 v106, 0, v244, s[94:95]
	v_cndmask_b32_e64 v114, 0, v236, s[92:93]
	v_cndmask_b32_e64 v107, 0, v245, s[94:95]
	v_cndmask_b32_e64 v115, 0, v237, s[92:93]
	v_cndmask_b32_e64 v108, 0, v246, s[94:95]
	v_cndmask_b32_e64 v116, 0, v238, s[92:93]
	v_cndmask_b32_e64 v109, 0, v247, s[94:95]
	v_cndmask_b32_e64 v117, 0, v239, s[92:93]
	v_cndmask_b32_e64 v110, 0, v248, s[94:95]
	v_cndmask_b32_e64 v118, 0, v240, s[92:93]
	v_cndmask_b32_e64 v111, 0, v249, s[94:95]
	v_cndmask_b32_e64 v119, 0, v241, s[92:93]
	v_mov_b32_e32 v98, 0xc0135761
	s_mul_i32 s73, s28, 0x160000
	s_add_u32 s80, s86, 0x9e00000
	s_addc_u32 s81, s87, 0
	s_add_u32 s80, s80, s73
	s_addc_u32 s81, s81, 0
	s_waitcnt lgkmcnt(0)
	s_cmp_lg_u32 s71, 0
	s_cbranch_scc1 .Lepi5_noedge0
	s_movk_i32 s75, 0x2c00
	v_mad_u32_u24 v99, v200, s75, v213
	s_mul_i32 s73, s28, 0xb000
	s_add_u32 s88, s86, 0x4000000
	s_addc_u32 s89, s87, 0
	s_add_u32 s88, s88, s73
	s_addc_u32 s89, s89, 0
	s_mul_i32 s73, s28, 0x5800
	s_add_u32 s34, s86, 0x4400000
	s_addc_u32 s35, s87, 0
	s_add_u32 s34, s34, s73
	s_addc_u32 s35, s35, 0
	s_mov_b64 exec, s[92:93]
	global_store_dwordx4 v99, v[148:151], s[88:89]
	global_store_dwordx4 v99, v[62:65], s[88:89] offset:16
	global_store_dwordx4 v99, v[144:147], s[34:35]
	global_store_dwordx4 v99, v[58:61], s[34:35] offset:16
	s_mov_b64 exec, -1

;     __device__ __forceinline__ void operator()(const f32x4 (&acc)[2][2][4][2], const Unit& u, int wr, int wc, int fr, int fq) const {
;     ...
;         float rstd[2][4];
; #pragma unroll
;         for (int ai = 0; ai < 2; ++ai)
; #pragma unroll
;             for (int m = 0; m < 4; ++m) rstd[ai][m] = RSTD[u.idx * 256 + ai * HALF + wr * 64 + m * 16 + fr];
;     ...
;                     } else {
;                         const int t = fr & 7, bb = (r - 16384) >> 3;
; #pragma unroll
;                         for (int e2 = 0; e2 < 4; ++e2) { p1[e2] = ror1(a[e2]); p2[e2] = ror2(a[e2]); }
;                         if (t < 2) { const f32x4 h1 = *(const f32x4*)(state_conv + ((size_t)bb * 2 + 1) * FF + j0 + 4 * n);
;                             if (t == 0) { p1 = h1; p2 = *(const f32x4*)(state_conv + ((size_t)bb * 2) * FF + j0 + 4 * n); } else p2 = h1; }
;                         if (t >= 6) *(f32x4*)(o_conv_s + ((size_t)bb * 2 + (t - 6)) * FF + j0 + 4 * n) = a;
.Lepi5_smp:
	v_readfirstlane_b32 s70, v0
	v_readlane_b32 s82, v254, 13
	v_readlane_b32 s83, v254, 14
	v_readlane_b32 s86, v254, 19
	v_readlane_b32 s87, v254, 20
	v_readlane_b32 s88, v254, 58
	v_readlane_b32 s89, v254, 59
	v_and_b32_e32 v200, 15, v202
	v_lshrrev_b32_e32 v201, 4, v202
	v_and_b32_e32 v191, 7, v202
	s_nop 0
	v_cmp_eq_u32_e64 s[90:91], 0, v191
	v_cmp_eq_u32_e64 s[92:93], 1, v191
	v_cmp_gt_u32_e64 s[94:95], 2, v191
	v_cmp_lt_u32_e64 s[84:85], 5, v191
	s_lshr_b32 s70, s70, 6
	s_lshr_b32 s71, s70, 2
	s_and_b32 s72, s70, 3
	s_sub_u32 s86, s86, 0x4000
	s_subb_u32 s87, s87, 0
	s_lshl_b32 s73, s10, 7
	s_lshl_b32 s74, s72, 5
	s_add_i32 s73, s73, s74
	v_lshl_add_u32 v213, v201, 3, s73
	v_lshlrev_b32_e32 v213, 2, v213
	s_lshl_b32 s73, s11, 10
	s_lshl_b32 s74, s71, 8
	s_add_i32 s73, s73, s74
	s_add_i32 s73, s73, 0x22000
	v_lshl_add_u32 v99, v200, 2, s73
	ds_read2_b32 v[152:153], v99 offset1:16
	ds_read2_b32 v[154:155], v99 offset0:32 offset1:48
	ds_read2_b32 v[156:157], v99 offset0:128 offset1:144
	ds_read2_b32 v[158:159], v99 offset0:160 offset1:176
	s_mul_i32 s74, s71, 0x58000
	v_lshrrev_b32_e32 v212, 1, v213
	v_add_u32_e32 v212, s74, v212
	s_movk_i32 s75, 0x1600
	v_mad_u32_u24 v212, v200, s75, v212
	v_lshrrev_b32_e32 v99, 3, v200
	s_movk_i32 s75, 0x5800
	v_mad_u32_u24 v188, v99, s75, v213
	v_add_u32_e32 v189, 0x2c00, v188
	v_lshl_add_u32 v99, v99, 1, v191
	v_add_u32_e32 v99, -6, v99
	s_movk_i32 s75, 0x2c00
	v_mad_u32_u24 v190, v99, s75, v213
	v_mov_b32_e32 v104, 0
	v_mov_b32_e32 v105, 0
	v_mov_b32_e32 v106, 0
	v_mov_b32_e32 v107, 0
	v_mov_b32_e32 v108, 0
	v_mov_b32_e32 v109, 0
	v_mov_b32_e32 v110, 0
	v_mov_b32_e32 v111, 0
	v_mov_b32_e32 v112, 0
	v_mov_b32_e32 v113, 0
	v_mov_b32_e32 v114, 0
	v_mov_b32_e32 v115, 0
	v_mov_b32_e32 v116, 0
	v_mov_b32_e32 v117, 0
	v_mov_b32_e32 v118, 0
	v_mov_b32_e32 v119, 0
	v_mov_b32_e32 v98, 0xc0135761
	s_sub_u32 s73, s28, 64
	s_lshl_b32 s73, s73, 5
	s_lshl_b32 s74, s71, 3
	s_add_i32 s73, s73, s74
	s_mul_i32 s73, s73, 0x5800
	s_add_u32 s82, s82, s73
	s_addc_u32 s83, s83, 0
	s_add_u32 s88, s88, 0x6c2a000
	s_addc_u32 s89, s89, 0
	s_add_u32 s88, s88, s73
	s_addc_u32 s89, s89, 0
	s_mul_i32 s73, s28, 0x160000
	s_add_u32 s80, s86, 0x9e00000
	s_addc_u32 s81, s87, 0
	s_add_u32 s80, s80, s73
	s_addc_u32 s81, s81, 0
	s_waitcnt lgkmcnt(0)
	v_pk_mul_f32 v[148:149], v[148:149], v[152:153] op_sel_hi:[1,0]
	v_pk_mul_f32 v[150:151], v[150:151], v[152:153] op_sel_hi:[1,0]
	v_pk_mul_f32 v[62:63], v[62:63], v[152:153] op_sel_hi:[1,0]
	v_pk_mul_f32 v[64:65], v[64:65], v[152:153] op_sel_hi:[1,0]
	v_pk_mul_f32 v[144:145], v[144:145], v[152:153] op_sel_hi:[1,0]
	v_pk_mul_f32 v[146:147], v[146:147], v[152:153] op_sel_hi:[1,0]
	v_pk_mul_f32 v[58:59], v[58:59], v[152:153] op_sel_hi:[1,0]
	v_pk_mul_f32 v[60:61], v[60:61], v[152:153] op_sel_hi:[1,0]
	v_pk_mul_f32 v[140:141], v[140:141], v[152:153] op_sel:[0,1] op_sel_hi:[1,1]
	v_pk_mul_f32 v[142:143], v[142:143], v[152:153] op_sel:[0,1] op_sel_hi:[1,1]
	v_pk_mul_f32 v[54:55], v[54:55], v[152:153] op_sel:[0,1] op_sel_hi:[1,1]
	v_pk_mul_f32 v[56:57], v[56:57], v[152:153] op_sel:[0,1] op_sel_hi:[1,1]
	v_pk_mul_f32 v[136:137], v[136:137], v[152:153] op_sel:[0,1] op_sel_hi:[1,1]
	v_pk_mul_f32 v[138:139], v[138:139], v[152:153] op_sel:[0,1] op_sel_hi:[1,1]
	v_pk_mul_f32 v[50:51], v[50:51], v[152:153] op_sel:[0,1] op_sel_hi:[1,1]
	v_pk_mul_f32 v[52:53], v[52:53], v[152:153] op_sel:[0,1] op_sel_hi:[1,1]
	v_pk_mul_f32 v[132:133], v[132:133], v[154:155] op_sel_hi:[1,0]
	v_pk_mul_f32 v[134:135], v[134:135], v[154:155] op_sel_hi:[1,0]
	v_pk_mul_f32 v[46:47], v[46:47], v[154:155] op_sel_hi:[1,0]
	v_pk_mul_f32 v[48:49], v[48:49], v[154:155] op_sel_hi:[1,0]
	v_pk_mul_f32 v[128:129], v[128:129], v[154:155] op_sel_hi:[1,0]
	v_pk_mul_f32 v[130:131], v[130:131], v[154:155] op_sel_hi:[1,0]
	v_pk_mul_f32 v[42:43], v[42:43], v[154:155] op_sel_hi:[1,0]
	v_pk_mul_f32 v[44:45], v[44:45], v[154:155] op_sel_hi:[1,0]
	v_pk_mul_f32 v[124:125], v[124:125], v[154:155] op_sel:[0,1] op_sel_hi:[1,1]
	v_pk_mul_f32 v[126:127], v[126:127], v[154:155] op_sel:[0,1] op_sel_hi:[1,1]
	v_pk_mul_f32 v[38:39], v[38:39], v[154:155] op_sel:[0,1] op_sel_hi:[1,1]
	v_pk_mul_f32 v[40:41], v[40:41], v[154:155] op_sel:[0,1] op_sel_hi:[1,1]
	v_pk_mul_f32 v[94:95], v[94:95], v[154:155] op_sel:[0,1] op_sel_hi:[1,1]
	v_pk_mul_f32 v[96:97], v[96:97], v[154:155] op_sel:[0,1] op_sel_hi:[1,1]
	v_pk_mul_f32 v[34:35], v[34:35], v[154:155] op_sel:[0,1] op_sel_hi:[1,1]
	v_pk_mul_f32 v[36:37], v[36:37], v[154:155] op_sel:[0,1] op_sel_hi:[1,1]
	v_pk_mul_f32 v[120:121], v[120:121], v[156:157] op_sel_hi:[1,0]
	v_pk_mul_f32 v[122:123], v[122:123], v[156:157] op_sel_hi:[1,0]
	v_pk_mul_f32 v[30:31], v[30:31], v[156:157] op_sel_hi:[1,0]
	v_pk_mul_f32 v[32:33], v[32:33], v[156:157] op_sel_hi:[1,0]
	v_pk_mul_f32 v[100:101], v[100:101], v[156:157] op_sel_hi:[1,0]
	v_pk_mul_f32 v[102:103], v[102:103], v[156:157] op_sel_hi:[1,0]
	v_pk_mul_f32 v[26:27], v[26:27], v[156:157] op_sel_hi:[1,0]
	v_pk_mul_f32 v[28:29], v[28:29], v[156:157] op_sel_hi:[1,0]
	v_pk_mul_f32 v[88:89], v[88:89], v[156:157] op_sel:[0,1] op_sel_hi:[1,1]
	v_pk_mul_f32 v[90:91], v[90:91], v[156:157] op_sel:[0,1] op_sel_hi:[1,1]
	v_pk_mul_f32 v[22:23], v[22:23], v[156:157] op_sel:[0,1] op_sel_hi:[1,1]
	v_pk_mul_f32 v[24:25], v[24:25], v[156:157] op_sel:[0,1] op_sel_hi:[1,1]
	v_pk_mul_f32 v[82:83], v[82:83], v[156:157] op_sel:[0,1] op_sel_hi:[1,1]
	v_pk_mul_f32 v[84:85], v[84:85], v[156:157] op_sel:[0,1] op_sel_hi:[1,1]
	v_pk_mul_f32 v[18:19], v[18:19], v[156:157] op_sel:[0,1] op_sel_hi:[1,1]
	v_pk_mul_f32 v[20:21], v[20:21], v[156:157] op_sel:[0,1] op_sel_hi:[1,1]
; __device__ __forceinline__ unsigned cvt_pk_bf16(float lo, float hi) { unsigned r; asm volatile("v_cvt_pk_bf16_f32 %0, %1, %2" : "=v"(r) : "v"(lo), "v"(hi)); return r; }
; __device__ __forceinline__ float frcp(float x) { return __builtin_amdgcn_rcpf(x); }
;     __device__ __forceinline__ void operator()(const f32x4 (&acc)[2][2][4][2], const Unit& u, int wr, int wc, int fr, int fq) const {
;     ...
;                     } else {
;                         const int t = fr & 7, bb = (r - 16384) >> 3;
; #pragma unroll
;                         for (int e2 = 0; e2 < 4; ++e2) { p1[e2] = ror1(a[e2]); p2[e2] = ror2(a[e2]); }
;                         if (t < 2) { const f32x4 h1 = *(const f32x4*)(state_conv + ((size_t)bb * 2 + 1) * FF + j0 + 4 * n);
;                             if (t == 0) { p1 = h1; p2 = *(const f32x4*)(state_conv + ((size_t)bb * 2) * FF + j0 + 4 * n); } else p2 = h1; }
;                         if (t >= 6) *(f32x4*)(o_conv_s + ((size_t)bb * 2 + (t - 6)) * FF + j0 + 4 * n) = a;
;                     }
;                     f32x4 hv;
; #pragma unroll
;                     for (int e2 = 0; e2 < 1; ++e2) {
;                         const f32x4 c4 = cb + w0 * p2 + w1 * p1 + w2 * a;
;                         const f32x4 z = c4 * ((c4 * c4) * (-0.10294324f) + (-2.3022082f));
;                         f32x4 den; den[0] = 1.f + __builtin_amdgcn_exp2f(z[0]); den[1] = 1.f + __builtin_amdgcn_exp2f(z[1]); den[2] = 1.f + __builtin_amdgcn_exp2f(z[2]); den[3] = 1.f + __builtin_amdgcn_exp2f(z[3]);
;                         f32x4 rc; rc[0] = frcp(den[0]); rc[1] = frcp(den[1]); rc[2] = frcp(den[2]); rc[3] = frcp(den[3]);
;                         hv = (c4 * rc) * b; }
;                     const u32x2 pkv = (u32x2){cvt_pk_bf16(hv[0], hv[1]), cvt_pk_bf16(hv[2], hv[3])};
;                     if (n == 0) pk0[ai][m] = pkv; else *(u32x4*)(HID + (size_t)r * FF + j0) = (u32x4){pk0[ai][m][0], pk0[ai][m][1], pkv[0], pkv[1]};
	v_pk_mul_f32 v[78:79], v[78:79], v[158:159] op_sel_hi:[1,0]
	v_pk_mul_f32 v[80:81], v[80:81], v[158:159] op_sel_hi:[1,0]
	v_pk_mul_f32 v[14:15], v[14:15], v[158:159] op_sel_hi:[1,0]
	v_pk_mul_f32 v[16:17], v[16:17], v[158:159] op_sel_hi:[1,0]
	v_pk_mul_f32 v[70:71], v[70:71], v[158:159] op_sel_hi:[1,0]
	v_pk_mul_f32 v[72:73], v[72:73], v[158:159] op_sel_hi:[1,0]
	v_pk_mul_f32 v[10:11], v[10:11], v[158:159] op_sel_hi:[1,0]
	v_pk_mul_f32 v[12:13], v[12:13], v[158:159] op_sel_hi:[1,0]
	v_pk_mul_f32 v[74:75], v[74:75], v[158:159] op_sel:[0,1] op_sel_hi:[1,1]
	v_pk_mul_f32 v[76:77], v[76:77], v[158:159] op_sel:[0,1] op_sel_hi:[1,1]
	v_pk_mul_f32 v[6:7], v[6:7], v[158:159] op_sel:[0,1] op_sel_hi:[1,1]
	v_pk_mul_f32 v[8:9], v[8:9], v[158:159] op_sel:[0,1] op_sel_hi:[1,1]
	v_pk_mul_f32 v[66:67], v[66:67], v[158:159] op_sel:[0,1] op_sel_hi:[1,1]
	v_pk_mul_f32 v[68:69], v[68:69], v[158:159] op_sel:[0,1] op_sel_hi:[1,1]
	v_pk_mul_f32 v[2:3], v[2:3], v[158:159] op_sel:[0,1] op_sel_hi:[1,1]
	v_pk_mul_f32 v[4:5], v[4:5], v[158:159] op_sel:[0,1] op_sel_hi:[1,1]
	s_and_b32 s73, s11, 1
	s_lshl_b32 s73, s73, 11
	s_add_i32 s73, s73, 0x24000
	s_lshl_b32 s74, s72, 7
	s_add_i32 s73, s73, s74
	v_lshl_add_u32 v99, v201, 5, s73
	ds_read_b128 v[226:229], v99 offset:0
	ds_read_b128 v[238:241], v99 offset:512
	ds_read_b128 v[234:237], v99 offset:1024
	ds_read_b128 v[230:233], v99 offset:1536
	s_mov_b64 s[34:35], s[82:83]
	s_mov_b64 s[42:43], s[88:89]
	s_mov_b64 exec, s[94:95]
	global_load_dwordx4 v[108:111], v189, s[34:35]
	s_mov_b64 exec, s[90:91]
	global_load_dwordx4 v[104:107], v188, s[34:35]
	s_mov_b64 exec, -1
	s_waitcnt lgkmcnt(0)
	v_cndmask_b32_e64 v242, v234, 0, s[90:91]
	v_cndmask_b32_e64 v246, v238, 0, s[94:95]
	v_cndmask_b32_e64 v250, 0, v238, s[92:93]
	v_cndmask_b32_e64 v204, 0, v238, s[90:91]
	v_cndmask_b32_e64 v243, v235, 0, s[90:91]
	v_cndmask_b32_e64 v247, v239, 0, s[94:95]
	v_cndmask_b32_e64 v251, 0, v239, s[92:93]
	v_cndmask_b32_e64 v205, 0, v239, s[90:91]
	v_cndmask_b32_e64 v244, v236, 0, s[90:91]
	v_cndmask_b32_e64 v248, v240, 0, s[94:95]
	v_cndmask_b32_e64 v252, 0, v240, s[92:93]
	v_cndmask_b32_e64 v206, 0, v240, s[90:91]
	v_cndmask_b32_e64 v245, v237, 0, s[90:91]
	v_cndmask_b32_e64 v249, v241, 0, s[94:95]
	v_cndmask_b32_e64 v253, 0, v241, s[92:93]
	v_cndmask_b32_e64 v207, 0, v241, s[90:91]
	v_cndmask_b32_e64 v250, v250, v234, s[90:91]
	v_cndmask_b32_e64 v251, v251, v235, s[90:91]
	v_cndmask_b32_e64 v252, v252, v236, s[90:91]
	v_cndmask_b32_e64 v253, v253, v237, s[90:91]
	s_add_u32 s34, s34, 0xb000
	s_addc_u32 s35, s35, 0
	s_mov_b64 exec, s[94:95]
	global_load_dwordx4 v[116:119], v189, s[34:35]
	s_mov_b64 exec, s[90:91]
	global_load_dwordx4 v[112:115], v188, s[34:35]
	s_mov_b64 exec, -1
	s_waitcnt vmcnt(2)
	v_fma_f32 v208, v148, v230, v226
	v_fma_f32 v209, v149, v231, v227
	v_fma_f32 v210, v150, v232, v228
	v_fma_f32 v211, v151, v233, v229
	v_fmac_f32_dpp v208, v148, v242 row_shr:1 row_mask:0xf bank_mask:0xf
	v_fmac_f32_dpp v209, v149, v243 row_shr:1 row_mask:0xf bank_mask:0xf
	v_fmac_f32_dpp v210, v150, v244 row_shr:1 row_mask:0xf bank_mask:0xf
	v_fmac_f32_dpp v211, v151, v245 row_shr:1 row_mask:0xf bank_mask:0xf
	v_fmac_f32_dpp v208, v148, v246 row_shr:2 row_mask:0xf bank_mask:0xf
	v_fmac_f32_dpp v209, v149, v247 row_shr:2 row_mask:0xf bank_mask:0xf
	v_fmac_f32_dpp v210, v150, v248 row_shr:2 row_mask:0xf bank_mask:0xf
	v_fmac_f32_dpp v211, v151, v249 row_shr:2 row_mask:0xf bank_mask:0xf
	v_fmac_f32_e32 v208, v108, v250
	v_fmac_f32_e32 v209, v109, v251
	v_fmac_f32_e32 v210, v110, v252
	v_fmac_f32_e32 v211, v111, v253
	v_fmac_f32_e32 v208, v104, v204
	v_fmac_f32_e32 v209, v105, v205
	v_fmac_f32_e32 v210, v106, v206
	v_fmac_f32_e32 v211, v107, v207
	v_mul_f32_e32 v86, v208, v208
	v_mul_f32_e32 v87, v209, v209
	v_mul_f32_e32 v92, v210, v210
	v_mul_f32_e32 v93, v211, v211
	v_fmamk_f32 v86, v86, 0xbdd2d3e8, v98
	v_fmamk_f32 v87, v87, 0xbdd2d3e8, v98
	v_fmamk_f32 v92, v92, 0xbdd2d3e8, v98
	v_fmamk_f32 v93, v93, 0xbdd2d3e8, v98
	v_mul_f32_e32 v86, v208, v86
	v_mul_f32_e32 v87, v209, v87
	v_mul_f32_e32 v92, v210, v92
	v_mul_f32_e32 v93, v211, v93
	v_exp_f32_e32 v86, v86
	v_exp_f32_e32 v87, v87
	v_exp_f32_e32 v92, v92
	v_exp_f32_e32 v93, v93
	v_mul_f32_e32 v208, v208, v144
	v_mul_f32_e32 v209, v209, v145
	v_mul_f32_e32 v210, v210, v146
	v_mul_f32_e32 v211, v211, v147
	v_add_f32_e32 v86, 1.0, v86
	v_add_f32_e32 v87, 1.0, v87
	v_add_f32_e32 v92, 1.0, v92
	v_add_f32_e32 v93, 1.0, v93
	v_rcp_f32_e32 v86, v86
	v_rcp_f32_e32 v87, v87
	v_rcp_f32_e32 v92, v92
	v_rcp_f32_e32 v93, v93
	s_nop 0
	v_mul_f32_e32 v208, v208, v86
	v_mul_f32_e32 v209, v209, v87
	v_mul_f32_e32 v210, v210, v92
	v_mul_f32_e32 v211, v211, v93
	v_cvt_pk_bf16_f32 v144, v208, v209
	v_cvt_pk_bf16_f32 v145, v210, v211
	s_mov_b64 exec, s[84:85]
	global_store_dwordx4 v190, v[148:151], s[42:43]
	s_mov_b64 exec, -1
	s_add_u32 s42, s42, 0xb000
	s_addc_u32 s43, s43, 0
	s_add_u32 s34, s34, 0xb000
	s_addc_u32 s35, s35, 0
	s_mov_b64 exec, s[94:95]
	global_load_dwordx4 v[108:111], v189, s[34:35]
	s_mov_b64 exec, s[90:91]
	global_load_dwordx4 v[104:107], v188, s[34:35]
	s_mov_b64 exec, -1
	s_waitcnt vmcnt(3)
; __device__ __forceinline__ unsigned cvt_pk_bf16(float lo, float hi) { unsigned r; asm volatile("v_cvt_pk_bf16_f32 %0, %1, %2" : "=v"(r) : "v"(lo), "v"(hi)); return r; }
; __device__ __forceinline__ float frcp(float x) { return __builtin_amdgcn_rcpf(x); }
;     __device__ __forceinline__ void operator()(const f32x4 (&acc)[2][2][4][2], const Unit& u, int wr, int wc, int fr, int fq) const {
;     ...
;                         const int t = fr & 7, bb = (r - 16384) >> 3;
; #pragma unroll
;                         for (int e2 = 0; e2 < 4; ++e2) { p1[e2] = ror1(a[e2]); p2[e2] = ror2(a[e2]); }
;                         if (t < 2) { const f32x4 h1 = *(const f32x4*)(state_conv + ((size_t)bb * 2 + 1) * FF + j0 + 4 * n);
;                             if (t == 0) { p1 = h1; p2 = *(const f32x4*)(state_conv + ((size_t)bb * 2) * FF + j0 + 4 * n); } else p2 = h1; }
;                         if (t >= 6) *(f32x4*)(o_conv_s + ((size_t)bb * 2 + (t - 6)) * FF + j0 + 4 * n) = a;
;                     }
;                     f32x4 hv;
; #pragma unroll
;                     for (int e2 = 0; e2 < 1; ++e2) {
;                         const f32x4 c4 = cb + w0 * p2 + w1 * p1 + w2 * a;
;                         const f32x4 z = c4 * ((c4 * c4) * (-0.10294324f) + (-2.3022082f));
;                         f32x4 den; den[0] = 1.f + __builtin_amdgcn_exp2f(z[0]); den[1] = 1.f + __builtin_amdgcn_exp2f(z[1]); den[2] = 1.f + __builtin_amdgcn_exp2f(z[2]); den[3] = 1.f + __builtin_amdgcn_exp2f(z[3]);
;                         f32x4 rc; rc[0] = frcp(den[0]); rc[1] = frcp(den[1]); rc[2] = frcp(den[2]); rc[3] = frcp(den[3]);
;                         hv = (c4 * rc) * b; }
;                     const u32x2 pkv = (u32x2){cvt_pk_bf16(hv[0], hv[1]), cvt_pk_bf16(hv[2], hv[3])};
;                     if (n == 0) pk0[ai][m] = pkv; else *(u32x4*)(HID + (size_t)r * FF + j0) = (u32x4){pk0[ai][m][0], pk0[ai][m][1], pkv[0], pkv[1]};
	v_fma_f32 v208, v140, v230, v226
	v_fma_f32 v209, v141, v231, v227
	v_fma_f32 v210, v142, v232, v228
	v_fma_f32 v211, v143, v233, v229
	v_fmac_f32_dpp v208, v140, v242 row_shr:1 row_mask:0xf bank_mask:0xf
	v_fmac_f32_dpp v209, v141, v243 row_shr:1 row_mask:0xf bank_mask:0xf
	v_fmac_f32_dpp v210, v142, v244 row_shr:1 row_mask:0xf bank_mask:0xf
	v_fmac_f32_dpp v211, v143, v245 row_shr:1 row_mask:0xf bank_mask:0xf
	v_fmac_f32_dpp v208, v140, v246 row_shr:2 row_mask:0xf bank_mask:0xf
	v_fmac_f32_dpp v209, v141, v247 row_shr:2 row_mask:0xf bank_mask:0xf
	v_fmac_f32_dpp v210, v142, v248 row_shr:2 row_mask:0xf bank_mask:0xf
	v_fmac_f32_dpp v211, v143, v249 row_shr:2 row_mask:0xf bank_mask:0xf
	v_fmac_f32_e32 v208, v116, v250
	v_fmac_f32_e32 v209, v117, v251
	v_fmac_f32_e32 v210, v118, v252
	v_fmac_f32_e32 v211, v119, v253
	v_fmac_f32_e32 v208, v112, v204
	v_fmac_f32_e32 v209, v113, v205
	v_fmac_f32_e32 v210, v114, v206
	v_fmac_f32_e32 v211, v115, v207
	v_mul_f32_e32 v86, v208, v208
	v_mul_f32_e32 v87, v209, v209
	v_mul_f32_e32 v92, v210, v210
	v_mul_f32_e32 v93, v211, v211
	v_fmamk_f32 v86, v86, 0xbdd2d3e8, v98
	v_fmamk_f32 v87, v87, 0xbdd2d3e8, v98
	v_fmamk_f32 v92, v92, 0xbdd2d3e8, v98
	v_fmamk_f32 v93, v93, 0xbdd2d3e8, v98
	v_mul_f32_e32 v86, v208, v86
	v_mul_f32_e32 v87, v209, v87
	v_mul_f32_e32 v92, v210, v92
	v_mul_f32_e32 v93, v211, v93
	v_exp_f32_e32 v86, v86
	v_exp_f32_e32 v87, v87
	v_exp_f32_e32 v92, v92
	v_exp_f32_e32 v93, v93
	v_mul_f32_e32 v208, v208, v136
	v_mul_f32_e32 v209, v209, v137
	v_mul_f32_e32 v210, v210, v138
	v_mul_f32_e32 v211, v211, v139
	v_add_f32_e32 v86, 1.0, v86
	v_add_f32_e32 v87, 1.0, v87
	v_add_f32_e32 v92, 1.0, v92
	v_add_f32_e32 v93, 1.0, v93
	v_rcp_f32_e32 v86, v86
	v_rcp_f32_e32 v87, v87
	v_rcp_f32_e32 v92, v92
	v_rcp_f32_e32 v93, v93
	s_nop 0
	v_mul_f32_e32 v208, v208, v86
	v_mul_f32_e32 v209, v209, v87
	v_mul_f32_e32 v210, v210, v92
	v_mul_f32_e32 v211, v211, v93
	v_cvt_pk_bf16_f32 v136, v208, v209
	v_cvt_pk_bf16_f32 v137, v210, v211
	s_mov_b64 exec, s[84:85]
	global_store_dwordx4 v190, v[140:143], s[42:43]
	s_mov_b64 exec, -1
	s_add_u32 s42, s42, 0xb000
	s_addc_u32 s43, s43, 0
	s_add_u32 s34, s34, 0xb000
	s_addc_u32 s35, s35, 0
	s_mov_b64 exec, s[94:95]
	global_load_dwordx4 v[116:119], v189, s[34:35]
	s_mov_b64 exec, s[90:91]
	global_load_dwordx4 v[112:115], v188, s[34:35]
	s_mov_b64 exec, -1
	s_waitcnt vmcnt(3)
	v_fma_f32 v208, v132, v230, v226
	v_fma_f32 v209, v133, v231, v227
	v_fma_f32 v210, v134, v232, v228
	v_fma_f32 v211, v135, v233, v229
	v_fmac_f32_dpp v208, v132, v242 row_shr:1 row_mask:0xf bank_mask:0xf
	v_fmac_f32_dpp v209, v133, v243 row_shr:1 row_mask:0xf bank_mask:0xf
	v_fmac_f32_dpp v210, v134, v244 row_shr:1 row_mask:0xf bank_mask:0xf
	v_fmac_f32_dpp v211, v135, v245 row_shr:1 row_mask:0xf bank_mask:0xf
	v_fmac_f32_dpp v208, v132, v246 row_shr:2 row_mask:0xf bank_mask:0xf
	v_fmac_f32_dpp v209, v133, v247 row_shr:2 row_mask:0xf bank_mask:0xf
	v_fmac_f32_dpp v210, v134, v248 row_shr:2 row_mask:0xf bank_mask:0xf
	v_fmac_f32_dpp v211, v135, v249 row_shr:2 row_mask:0xf bank_mask:0xf
	v_fmac_f32_e32 v208, v108, v250
	v_fmac_f32_e32 v209, v109, v251
	v_fmac_f32_e32 v210, v110, v252
	v_fmac_f32_e32 v211, v111, v253
	v_fmac_f32_e32 v208, v104, v204
	v_fmac_f32_e32 v209, v105, v205
	v_fmac_f32_e32 v210, v106, v206
	v_fmac_f32_e32 v211, v107, v207
	v_mul_f32_e32 v86, v208, v208
	v_mul_f32_e32 v87, v209, v209
	v_mul_f32_e32 v92, v210, v210
	v_mul_f32_e32 v93, v211, v211
	v_fmamk_f32 v86, v86, 0xbdd2d3e8, v98
	v_fmamk_f32 v87, v87, 0xbdd2d3e8, v98
	v_fmamk_f32 v92, v92, 0xbdd2d3e8, v98
	v_fmamk_f32 v93, v93, 0xbdd2d3e8, v98
	v_mul_f32_e32 v86, v208, v86
	v_mul_f32_e32 v87, v209, v87
	v_mul_f32_e32 v92, v210, v92
	v_mul_f32_e32 v93, v211, v93
	v_exp_f32_e32 v86, v86
	v_exp_f32_e32 v87, v87
	v_exp_f32_e32 v92, v92
	v_exp_f32_e32 v93, v93
	v_mul_f32_e32 v208, v208, v128
	v_mul_f32_e32 v209, v209, v129
	v_mul_f32_e32 v210, v210, v130
	v_mul_f32_e32 v211, v211, v131
	v_add_f32_e32 v86, 1.0, v86
	v_add_f32_e32 v87, 1.0, v87
	v_add_f32_e32 v92, 1.0, v92
	v_add_f32_e32 v93, 1.0, v93
	v_rcp_f32_e32 v86, v86
	v_rcp_f32_e32 v87, v87
	v_rcp_f32_e32 v92, v92
	v_rcp_f32_e32 v93, v93
	s_nop 0
	v_mul_f32_e32 v208, v208, v86
	v_mul_f32_e32 v209, v209, v87
	v_mul_f32_e32 v210, v210, v92
	v_mul_f32_e32 v211, v211, v93
	v_cvt_pk_bf16_f32 v128, v208, v209
	v_cvt_pk_bf16_f32 v129, v210, v211
	s_mov_b64 exec, s[84:85]
	global_store_dwordx4 v190, v[132:135], s[42:43]
	s_mov_b64 exec, -1
	s_add_u32 s42, s42, 0xb000
	s_addc_u32 s43, s43, 0
	s_add_u32 s34, s34, 0x37000
	s_addc_u32 s35, s35, 0
	s_mov_b64 exec, s[94:95]
	global_load_dwordx4 v[108:111], v189, s[34:35]
	s_mov_b64 exec, s[90:91]
	global_load_dwordx4 v[104:107], v188, s[34:35]
	s_mov_b64 exec, -1
	s_waitcnt vmcnt(3)
; __device__ __forceinline__ unsigned cvt_pk_bf16(float lo, float hi) { unsigned r; asm volatile("v_cvt_pk_bf16_f32 %0, %1, %2" : "=v"(r) : "v"(lo), "v"(hi)); return r; }
; __device__ __forceinline__ float frcp(float x) { return __builtin_amdgcn_rcpf(x); }
;     __device__ __forceinline__ void operator()(const f32x4 (&acc)[2][2][4][2], const Unit& u, int wr, int wc, int fr, int fq) const {
;     ...
;                         const int t = fr & 7, bb = (r - 16384) >> 3;
; #pragma unroll
;                         for (int e2 = 0; e2 < 4; ++e2) { p1[e2] = ror1(a[e2]); p2[e2] = ror2(a[e2]); }
;                         if (t < 2) { const f32x4 h1 = *(const f32x4*)(state_conv + ((size_t)bb * 2 + 1) * FF + j0 + 4 * n);
;                             if (t == 0) { p1 = h1; p2 = *(const f32x4*)(state_conv + ((size_t)bb * 2) * FF + j0 + 4 * n); } else p2 = h1; }
;                         if (t >= 6) *(f32x4*)(o_conv_s + ((size_t)bb * 2 + (t - 6)) * FF + j0 + 4 * n) = a;
;                     }
;                     f32x4 hv;
; #pragma unroll
;                     for (int e2 = 0; e2 < 1; ++e2) {
;                         const f32x4 c4 = cb + w0 * p2 + w1 * p1 + w2 * a;
;                         const f32x4 z = c4 * ((c4 * c4) * (-0.10294324f) + (-2.3022082f));
;                         f32x4 den; den[0] = 1.f + __builtin_amdgcn_exp2f(z[0]); den[1] = 1.f + __builtin_amdgcn_exp2f(z[1]); den[2] = 1.f + __builtin_amdgcn_exp2f(z[2]); den[3] = 1.f + __builtin_amdgcn_exp2f(z[3]);
;                         f32x4 rc; rc[0] = frcp(den[0]); rc[1] = frcp(den[1]); rc[2] = frcp(den[2]); rc[3] = frcp(den[3]);
;                         hv = (c4 * rc) * b; }
;                     const u32x2 pkv = (u32x2){cvt_pk_bf16(hv[0], hv[1]), cvt_pk_bf16(hv[2], hv[3])};
;                     if (n == 0) pk0[ai][m] = pkv; else *(u32x4*)(HID + (size_t)r * FF + j0) = (u32x4){pk0[ai][m][0], pk0[ai][m][1], pkv[0], pkv[1]};
	v_fma_f32 v208, v124, v230, v226
	v_fma_f32 v209, v125, v231, v227
	v_fma_f32 v210, v126, v232, v228
	v_fma_f32 v211, v127, v233, v229
	v_fmac_f32_dpp v208, v124, v242 row_shr:1 row_mask:0xf bank_mask:0xf
	v_fmac_f32_dpp v209, v125, v243 row_shr:1 row_mask:0xf bank_mask:0xf
	v_fmac_f32_dpp v210, v126, v244 row_shr:1 row_mask:0xf bank_mask:0xf
	v_fmac_f32_dpp v211, v127, v245 row_shr:1 row_mask:0xf bank_mask:0xf
	v_fmac_f32_dpp v208, v124, v246 row_shr:2 row_mask:0xf bank_mask:0xf
	v_fmac_f32_dpp v209, v125, v247 row_shr:2 row_mask:0xf bank_mask:0xf
	v_fmac_f32_dpp v210, v126, v248 row_shr:2 row_mask:0xf bank_mask:0xf
	v_fmac_f32_dpp v211, v127, v249 row_shr:2 row_mask:0xf bank_mask:0xf
	v_fmac_f32_e32 v208, v116, v250
	v_fmac_f32_e32 v209, v117, v251
	v_fmac_f32_e32 v210, v118, v252
	v_fmac_f32_e32 v211, v119, v253
	v_fmac_f32_e32 v208, v112, v204
	v_fmac_f32_e32 v209, v113, v205
	v_fmac_f32_e32 v210, v114, v206
	v_fmac_f32_e32 v211, v115, v207
	v_mul_f32_e32 v86, v208, v208
	v_mul_f32_e32 v87, v209, v209
	v_mul_f32_e32 v92, v210, v210
	v_mul_f32_e32 v93, v211, v211
	v_fmamk_f32 v86, v86, 0xbdd2d3e8, v98
	v_fmamk_f32 v87, v87, 0xbdd2d3e8, v98
	v_fmamk_f32 v92, v92, 0xbdd2d3e8, v98
	v_fmamk_f32 v93, v93, 0xbdd2d3e8, v98
	v_mul_f32_e32 v86, v208, v86
	v_mul_f32_e32 v87, v209, v87
	v_mul_f32_e32 v92, v210, v92
	v_mul_f32_e32 v93, v211, v93
	v_exp_f32_e32 v86, v86
	v_exp_f32_e32 v87, v87
	v_exp_f32_e32 v92, v92
	v_exp_f32_e32 v93, v93
	v_mul_f32_e32 v208, v208, v94
	v_mul_f32_e32 v209, v209, v95
	v_mul_f32_e32 v210, v210, v96
	v_mul_f32_e32 v211, v211, v97
	v_add_f32_e32 v86, 1.0, v86
	v_add_f32_e32 v87, 1.0, v87
	v_add_f32_e32 v92, 1.0, v92
	v_add_f32_e32 v93, 1.0, v93
	v_rcp_f32_e32 v86, v86
	v_rcp_f32_e32 v87, v87
	v_rcp_f32_e32 v92, v92
	v_rcp_f32_e32 v93, v93
	s_nop 0
	v_mul_f32_e32 v208, v208, v86
	v_mul_f32_e32 v209, v209, v87
	v_mul_f32_e32 v210, v210, v92
	v_mul_f32_e32 v211, v211, v93
	v_cvt_pk_bf16_f32 v94, v208, v209
	v_cvt_pk_bf16_f32 v95, v210, v211
	s_mov_b64 exec, s[84:85]
	global_store_dwordx4 v190, v[124:127], s[42:43]
	s_mov_b64 exec, -1
	s_add_u32 s42, s42, 0x37000
	s_addc_u32 s43, s43, 0
	s_add_u32 s34, s34, 0xb000
	s_addc_u32 s35, s35, 0
	s_mov_b64 exec, s[94:95]
	global_load_dwordx4 v[116:119], v189, s[34:35]
	s_mov_b64 exec, s[90:91]
	global_load_dwordx4 v[112:115], v188, s[34:35]
	s_mov_b64 exec, -1
	s_waitcnt vmcnt(3)
	v_fma_f32 v208, v120, v230, v226
	v_fma_f32 v209, v121, v231, v227
	v_fma_f32 v210, v122, v232, v228
	v_fma_f32 v211, v123, v233, v229
	v_fmac_f32_dpp v208, v120, v242 row_shr:1 row_mask:0xf bank_mask:0xf
	v_fmac_f32_dpp v209, v121, v243 row_shr:1 row_mask:0xf bank_mask:0xf
	v_fmac_f32_dpp v210, v122, v244 row_shr:1 row_mask:0xf bank_mask:0xf
	v_fmac_f32_dpp v211, v123, v245 row_shr:1 row_mask:0xf bank_mask:0xf
	v_fmac_f32_dpp v208, v120, v246 row_shr:2 row_mask:0xf bank_mask:0xf
	v_fmac_f32_dpp v209, v121, v247 row_shr:2 row_mask:0xf bank_mask:0xf
	v_fmac_f32_dpp v210, v122, v248 row_shr:2 row_mask:0xf bank_mask:0xf
	v_fmac_f32_dpp v211, v123, v249 row_shr:2 row_mask:0xf bank_mask:0xf
	v_fmac_f32_e32 v208, v108, v250
	v_fmac_f32_e32 v209, v109, v251
	v_fmac_f32_e32 v210, v110, v252
	v_fmac_f32_e32 v211, v111, v253
	v_fmac_f32_e32 v208, v104, v204
	v_fmac_f32_e32 v209, v105, v205
	v_fmac_f32_e32 v210, v106, v206
	v_fmac_f32_e32 v211, v107, v207
	v_mul_f32_e32 v86, v208, v208
	v_mul_f32_e32 v87, v209, v209
	v_mul_f32_e32 v92, v210, v210
	v_mul_f32_e32 v93, v211, v211
	v_fmamk_f32 v86, v86, 0xbdd2d3e8, v98
	v_fmamk_f32 v87, v87, 0xbdd2d3e8, v98
	v_fmamk_f32 v92, v92, 0xbdd2d3e8, v98
	v_fmamk_f32 v93, v93, 0xbdd2d3e8, v98
	v_mul_f32_e32 v86, v208, v86
	v_mul_f32_e32 v87, v209, v87
	v_mul_f32_e32 v92, v210, v92
	v_mul_f32_e32 v93, v211, v93
	v_exp_f32_e32 v86, v86
	v_exp_f32_e32 v87, v87
	v_exp_f32_e32 v92, v92
	v_exp_f32_e32 v93, v93
	v_mul_f32_e32 v208, v208, v100
	v_mul_f32_e32 v209, v209, v101
	v_mul_f32_e32 v210, v210, v102
	v_mul_f32_e32 v211, v211, v103
	v_add_f32_e32 v86, 1.0, v86
	v_add_f32_e32 v87, 1.0, v87
	v_add_f32_e32 v92, 1.0, v92
	v_add_f32_e32 v93, 1.0, v93
	v_rcp_f32_e32 v86, v86
	v_rcp_f32_e32 v87, v87
	v_rcp_f32_e32 v92, v92
	v_rcp_f32_e32 v93, v93
	s_nop 0
	v_mul_f32_e32 v208, v208, v86
	v_mul_f32_e32 v209, v209, v87
	v_mul_f32_e32 v210, v210, v92
	v_mul_f32_e32 v211, v211, v93
	v_cvt_pk_bf16_f32 v100, v208, v209
	v_cvt_pk_bf16_f32 v101, v210, v211
	s_mov_b64 exec, s[84:85]
	global_store_dwordx4 v190, v[120:123], s[42:43]
	s_mov_b64 exec, -1
	s_add_u32 s42, s42, 0xb000
	s_addc_u32 s43, s43, 0
	s_add_u32 s34, s34, 0xb000
	s_addc_u32 s35, s35, 0
	s_mov_b64 exec, s[94:95]
	global_load_dwordx4 v[108:111], v189, s[34:35]
	s_mov_b64 exec, s[90:91]
	global_load_dwordx4 v[104:107], v188, s[34:35]
	s_mov_b64 exec, -1
	s_waitcnt vmcnt(3)
; __device__ __forceinline__ unsigned cvt_pk_bf16(float lo, float hi) { unsigned r; asm volatile("v_cvt_pk_bf16_f32 %0, %1, %2" : "=v"(r) : "v"(lo), "v"(hi)); return r; }
; __device__ __forceinline__ float frcp(float x) { return __builtin_amdgcn_rcpf(x); }
;     __device__ __forceinline__ void operator()(const f32x4 (&acc)[2][2][4][2], const Unit& u, int wr, int wc, int fr, int fq) const {
;     ...
;                         const int t = fr & 7, bb = (r - 16384) >> 3;
; #pragma unroll
;                         for (int e2 = 0; e2 < 4; ++e2) { p1[e2] = ror1(a[e2]); p2[e2] = ror2(a[e2]); }
;                         if (t < 2) { const f32x4 h1 = *(const f32x4*)(state_conv + ((size_t)bb * 2 + 1) * FF + j0 + 4 * n);
;                             if (t == 0) { p1 = h1; p2 = *(const f32x4*)(state_conv + ((size_t)bb * 2) * FF + j0 + 4 * n); } else p2 = h1; }
;                         if (t >= 6) *(f32x4*)(o_conv_s + ((size_t)bb * 2 + (t - 6)) * FF + j0 + 4 * n) = a;
;                     }
;                     f32x4 hv;
; #pragma unroll
;                     for (int e2 = 0; e2 < 1; ++e2) {
;                         const f32x4 c4 = cb + w0 * p2 + w1 * p1 + w2 * a;
;                         const f32x4 z = c4 * ((c4 * c4) * (-0.10294324f) + (-2.3022082f));
;                         f32x4 den; den[0] = 1.f + __builtin_amdgcn_exp2f(z[0]); den[1] = 1.f + __builtin_amdgcn_exp2f(z[1]); den[2] = 1.f + __builtin_amdgcn_exp2f(z[2]); den[3] = 1.f + __builtin_amdgcn_exp2f(z[3]);
;                         f32x4 rc; rc[0] = frcp(den[0]); rc[1] = frcp(den[1]); rc[2] = frcp(den[2]); rc[3] = frcp(den[3]);
;                         hv = (c4 * rc) * b; }
;                     const u32x2 pkv = (u32x2){cvt_pk_bf16(hv[0], hv[1]), cvt_pk_bf16(hv[2], hv[3])};
;                     if (n == 0) pk0[ai][m] = pkv; else *(u32x4*)(HID + (size_t)r * FF + j0) = (u32x4){pk0[ai][m][0], pk0[ai][m][1], pkv[0], pkv[1]};
	v_fma_f32 v208, v88, v230, v226
	v_fma_f32 v209, v89, v231, v227
	v_fma_f32 v210, v90, v232, v228
	v_fma_f32 v211, v91, v233, v229
	v_fmac_f32_dpp v208, v88, v242 row_shr:1 row_mask:0xf bank_mask:0xf
	v_fmac_f32_dpp v209, v89, v243 row_shr:1 row_mask:0xf bank_mask:0xf
	v_fmac_f32_dpp v210, v90, v244 row_shr:1 row_mask:0xf bank_mask:0xf
	v_fmac_f32_dpp v211, v91, v245 row_shr:1 row_mask:0xf bank_mask:0xf
	v_fmac_f32_dpp v208, v88, v246 row_shr:2 row_mask:0xf bank_mask:0xf
	v_fmac_f32_dpp v209, v89, v247 row_shr:2 row_mask:0xf bank_mask:0xf
	v_fmac_f32_dpp v210, v90, v248 row_shr:2 row_mask:0xf bank_mask:0xf
	v_fmac_f32_dpp v211, v91, v249 row_shr:2 row_mask:0xf bank_mask:0xf
	v_fmac_f32_e32 v208, v116, v250
	v_fmac_f32_e32 v209, v117, v251
	v_fmac_f32_e32 v210, v118, v252
	v_fmac_f32_e32 v211, v119, v253
	v_fmac_f32_e32 v208, v112, v204
	v_fmac_f32_e32 v209, v113, v205
	v_fmac_f32_e32 v210, v114, v206
	v_fmac_f32_e32 v211, v115, v207
	v_mul_f32_e32 v86, v208, v208
	v_mul_f32_e32 v87, v209, v209
	v_mul_f32_e32 v92, v210, v210
	v_mul_f32_e32 v93, v211, v211
	v_fmamk_f32 v86, v86, 0xbdd2d3e8, v98
	v_fmamk_f32 v87, v87, 0xbdd2d3e8, v98
	v_fmamk_f32 v92, v92, 0xbdd2d3e8, v98
	v_fmamk_f32 v93, v93, 0xbdd2d3e8, v98
	v_mul_f32_e32 v86, v208, v86
	v_mul_f32_e32 v87, v209, v87
	v_mul_f32_e32 v92, v210, v92
	v_mul_f32_e32 v93, v211, v93
	v_exp_f32_e32 v86, v86
	v_exp_f32_e32 v87, v87
	v_exp_f32_e32 v92, v92
	v_exp_f32_e32 v93, v93
	v_mul_f32_e32 v208, v208, v82
	v_mul_f32_e32 v209, v209, v83
	v_mul_f32_e32 v210, v210, v84
	v_mul_f32_e32 v211, v211, v85
	v_add_f32_e32 v86, 1.0, v86
	v_add_f32_e32 v87, 1.0, v87
	v_add_f32_e32 v92, 1.0, v92
	v_add_f32_e32 v93, 1.0, v93
	v_rcp_f32_e32 v86, v86
	v_rcp_f32_e32 v87, v87
	v_rcp_f32_e32 v92, v92
	v_rcp_f32_e32 v93, v93
	s_nop 0
	v_mul_f32_e32 v208, v208, v86
	v_mul_f32_e32 v209, v209, v87
	v_mul_f32_e32 v210, v210, v92
	v_mul_f32_e32 v211, v211, v93
	v_cvt_pk_bf16_f32 v82, v208, v209
	v_cvt_pk_bf16_f32 v83, v210, v211
	s_mov_b64 exec, s[84:85]
	global_store_dwordx4 v190, v[88:91], s[42:43]
	s_mov_b64 exec, -1
	s_add_u32 s42, s42, 0xb000
	s_addc_u32 s43, s43, 0
	s_add_u32 s34, s34, 0xb000
	s_addc_u32 s35, s35, 0
	s_mov_b64 exec, s[94:95]
	global_load_dwordx4 v[116:119], v189, s[34:35]
	s_mov_b64 exec, s[90:91]
	global_load_dwordx4 v[112:115], v188, s[34:35]
	s_mov_b64 exec, -1
	s_waitcnt vmcnt(3)
	v_fma_f32 v208, v78, v230, v226
	v_fma_f32 v209, v79, v231, v227
	v_fma_f32 v210, v80, v232, v228
	v_fma_f32 v211, v81, v233, v229
	v_fmac_f32_dpp v208, v78, v242 row_shr:1 row_mask:0xf bank_mask:0xf
	v_fmac_f32_dpp v209, v79, v243 row_shr:1 row_mask:0xf bank_mask:0xf
	v_fmac_f32_dpp v210, v80, v244 row_shr:1 row_mask:0xf bank_mask:0xf
	v_fmac_f32_dpp v211, v81, v245 row_shr:1 row_mask:0xf bank_mask:0xf
	v_fmac_f32_dpp v208, v78, v246 row_shr:2 row_mask:0xf bank_mask:0xf
	v_fmac_f32_dpp v209, v79, v247 row_shr:2 row_mask:0xf bank_mask:0xf
	v_fmac_f32_dpp v210, v80, v248 row_shr:2 row_mask:0xf bank_mask:0xf
	v_fmac_f32_dpp v211, v81, v249 row_shr:2 row_mask:0xf bank_mask:0xf
	v_fmac_f32_e32 v208, v108, v250
	v_fmac_f32_e32 v209, v109, v251
	v_fmac_f32_e32 v210, v110, v252
	v_fmac_f32_e32 v211, v111, v253
	v_fmac_f32_e32 v208, v104, v204
	v_fmac_f32_e32 v209, v105, v205
	v_fmac_f32_e32 v210, v106, v206
	v_fmac_f32_e32 v211, v107, v207
	v_mul_f32_e32 v86, v208, v208
	v_mul_f32_e32 v87, v209, v209
	v_mul_f32_e32 v92, v210, v210
	v_mul_f32_e32 v93, v211, v211
	v_fmamk_f32 v86, v86, 0xbdd2d3e8, v98
	v_fmamk_f32 v87, v87, 0xbdd2d3e8, v98
	v_fmamk_f32 v92, v92, 0xbdd2d3e8, v98
	v_fmamk_f32 v93, v93, 0xbdd2d3e8, v98
	v_mul_f32_e32 v86, v208, v86
	v_mul_f32_e32 v87, v209, v87
	v_mul_f32_e32 v92, v210, v92
	v_mul_f32_e32 v93, v211, v93
	v_exp_f32_e32 v86, v86
	v_exp_f32_e32 v87, v87
	v_exp_f32_e32 v92, v92
	v_exp_f32_e32 v93, v93
	v_mul_f32_e32 v208, v208, v70
	v_mul_f32_e32 v209, v209, v71
	v_mul_f32_e32 v210, v210, v72
	v_mul_f32_e32 v211, v211, v73
	v_add_f32_e32 v86, 1.0, v86
	v_add_f32_e32 v87, 1.0, v87
	v_add_f32_e32 v92, 1.0, v92
	v_add_f32_e32 v93, 1.0, v93
	v_rcp_f32_e32 v86, v86
	v_rcp_f32_e32 v87, v87
	v_rcp_f32_e32 v92, v92
	v_rcp_f32_e32 v93, v93
	s_nop 0
	v_mul_f32_e32 v208, v208, v86
	v_mul_f32_e32 v209, v209, v87
	v_mul_f32_e32 v210, v210, v92
	v_mul_f32_e32 v211, v211, v93
	v_cvt_pk_bf16_f32 v70, v208, v209
	v_cvt_pk_bf16_f32 v71, v210, v211
	s_mov_b64 exec, s[84:85]
	global_store_dwordx4 v190, v[78:81], s[42:43]
	s_mov_b64 exec, -1
	s_add_u32 s42, s42, 0xb000
	s_addc_u32 s43, s43, 0
	s_waitcnt vmcnt(1)
; __device__ __forceinline__ unsigned cvt_pk_bf16(float lo, float hi) { unsigned r; asm volatile("v_cvt_pk_bf16_f32 %0, %1, %2" : "=v"(r) : "v"(lo), "v"(hi)); return r; }
; __device__ __forceinline__ float frcp(float x) { return __builtin_amdgcn_rcpf(x); }
;     __device__ __forceinline__ void operator()(const f32x4 (&acc)[2][2][4][2], const Unit& u, int wr, int wc, int fr, int fq) const {
;     ...
;                         const int t = fr & 7, bb = (r - 16384) >> 3;
; #pragma unroll
;                         for (int e2 = 0; e2 < 4; ++e2) { p1[e2] = ror1(a[e2]); p2[e2] = ror2(a[e2]); }
;                         if (t < 2) { const f32x4 h1 = *(const f32x4*)(state_conv + ((size_t)bb * 2 + 1) * FF + j0 + 4 * n);
;                             if (t == 0) { p1 = h1; p2 = *(const f32x4*)(state_conv + ((size_t)bb * 2) * FF + j0 + 4 * n); } else p2 = h1; }
;                         if (t >= 6) *(f32x4*)(o_conv_s + ((size_t)bb * 2 + (t - 6)) * FF + j0 + 4 * n) = a;
;                     }
;                     f32x4 hv;
; #pragma unroll
;                     for (int e2 = 0; e2 < 1; ++e2) {
;                         const f32x4 c4 = cb + w0 * p2 + w1 * p1 + w2 * a;
;                         const f32x4 z = c4 * ((c4 * c4) * (-0.10294324f) + (-2.3022082f));
;                         f32x4 den; den[0] = 1.f + __builtin_amdgcn_exp2f(z[0]); den[1] = 1.f + __builtin_amdgcn_exp2f(z[1]); den[2] = 1.f + __builtin_amdgcn_exp2f(z[2]); den[3] = 1.f + __builtin_amdgcn_exp2f(z[3]);
;                         f32x4 rc; rc[0] = frcp(den[0]); rc[1] = frcp(den[1]); rc[2] = frcp(den[2]); rc[3] = frcp(den[3]);
;                         hv = (c4 * rc) * b; }
;                     const u32x2 pkv = (u32x2){cvt_pk_bf16(hv[0], hv[1]), cvt_pk_bf16(hv[2], hv[3])};
;                     if (n == 0) pk0[ai][m] = pkv; else *(u32x4*)(HID + (size_t)r * FF + j0) = (u32x4){pk0[ai][m][0], pk0[ai][m][1], pkv[0], pkv[1]};
	v_fma_f32 v208, v74, v230, v226
	v_fma_f32 v209, v75, v231, v227
	v_fma_f32 v210, v76, v232, v228
	v_fma_f32 v211, v77, v233, v229
	v_fmac_f32_dpp v208, v74, v242 row_shr:1 row_mask:0xf bank_mask:0xf
	v_fmac_f32_dpp v209, v75, v243 row_shr:1 row_mask:0xf bank_mask:0xf
	v_fmac_f32_dpp v210, v76, v244 row_shr:1 row_mask:0xf bank_mask:0xf
	v_fmac_f32_dpp v211, v77, v245 row_shr:1 row_mask:0xf bank_mask:0xf
	v_fmac_f32_dpp v208, v74, v246 row_shr:2 row_mask:0xf bank_mask:0xf
	v_fmac_f32_dpp v209, v75, v247 row_shr:2 row_mask:0xf bank_mask:0xf
	v_fmac_f32_dpp v210, v76, v248 row_shr:2 row_mask:0xf bank_mask:0xf
	v_fmac_f32_dpp v211, v77, v249 row_shr:2 row_mask:0xf bank_mask:0xf
	v_fmac_f32_e32 v208, v116, v250
	v_fmac_f32_e32 v209, v117, v251
	v_fmac_f32_e32 v210, v118, v252
	v_fmac_f32_e32 v211, v119, v253
	v_fmac_f32_e32 v208, v112, v204
	v_fmac_f32_e32 v209, v113, v205
	v_fmac_f32_e32 v210, v114, v206
	v_fmac_f32_e32 v211, v115, v207
	v_mul_f32_e32 v86, v208, v208
	v_mul_f32_e32 v87, v209, v209
	v_mul_f32_e32 v92, v210, v210
	v_mul_f32_e32 v93, v211, v211
	v_fmamk_f32 v86, v86, 0xbdd2d3e8, v98
	v_fmamk_f32 v87, v87, 0xbdd2d3e8, v98
	v_fmamk_f32 v92, v92, 0xbdd2d3e8, v98
	v_fmamk_f32 v93, v93, 0xbdd2d3e8, v98
	v_mul_f32_e32 v86, v208, v86
	v_mul_f32_e32 v87, v209, v87
	v_mul_f32_e32 v92, v210, v92
	v_mul_f32_e32 v93, v211, v93
	v_exp_f32_e32 v86, v86
	v_exp_f32_e32 v87, v87
	v_exp_f32_e32 v92, v92
	v_exp_f32_e32 v93, v93
	v_mul_f32_e32 v208, v208, v66
	v_mul_f32_e32 v209, v209, v67
	v_mul_f32_e32 v210, v210, v68
	v_mul_f32_e32 v211, v211, v69
	v_add_f32_e32 v86, 1.0, v86
	v_add_f32_e32 v87, 1.0, v87
	v_add_f32_e32 v92, 1.0, v92
	v_add_f32_e32 v93, 1.0, v93
	v_rcp_f32_e32 v86, v86
	v_rcp_f32_e32 v87, v87
	v_rcp_f32_e32 v92, v92
	v_rcp_f32_e32 v93, v93
	s_nop 0
	v_mul_f32_e32 v208, v208, v86
	v_mul_f32_e32 v209, v209, v87
	v_mul_f32_e32 v210, v210, v92
	v_mul_f32_e32 v211, v211, v93
	v_cvt_pk_bf16_f32 v66, v208, v209
	v_cvt_pk_bf16_f32 v67, v210, v211
	s_mov_b64 exec, s[84:85]
	global_store_dwordx4 v190, v[74:77], s[42:43]
	s_mov_b64 exec, -1
	ds_read_b128 v[226:229], v99 offset:16
	ds_read_b128 v[238:241], v99 offset:528
	ds_read_b128 v[234:237], v99 offset:1040
	ds_read_b128 v[230:233], v99 offset:1552
	s_mov_b64 s[34:35], s[82:83]
	s_mov_b64 s[42:43], s[88:89]
	s_mov_b64 exec, s[94:95]
	global_load_dwordx4 v[108:111], v189, s[34:35] offset:16
	s_mov_b64 exec, s[90:91]
	global_load_dwordx4 v[104:107], v188, s[34:35] offset:16
	s_mov_b64 exec, -1
	s_waitcnt lgkmcnt(0)
	v_cndmask_b32_e64 v242, v234, 0, s[90:91]
	v_cndmask_b32_e64 v246, v238, 0, s[94:95]
	v_cndmask_b32_e64 v250, 0, v238, s[92:93]
	v_cndmask_b32_e64 v204, 0, v238, s[90:91]
	v_cndmask_b32_e64 v243, v235, 0, s[90:91]
	v_cndmask_b32_e64 v247, v239, 0, s[94:95]
	v_cndmask_b32_e64 v251, 0, v239, s[92:93]
	v_cndmask_b32_e64 v205, 0, v239, s[90:91]
	v_cndmask_b32_e64 v244, v236, 0, s[90:91]
	v_cndmask_b32_e64 v248, v240, 0, s[94:95]
	v_cndmask_b32_e64 v252, 0, v240, s[92:93]
	v_cndmask_b32_e64 v206, 0, v240, s[90:91]
	v_cndmask_b32_e64 v245, v237, 0, s[90:91]
	v_cndmask_b32_e64 v249, v241, 0, s[94:95]
	v_cndmask_b32_e64 v253, 0, v241, s[92:93]
	v_cndmask_b32_e64 v207, 0, v241, s[90:91]
	v_cndmask_b32_e64 v250, v250, v234, s[90:91]
	v_cndmask_b32_e64 v251, v251, v235, s[90:91]
	v_cndmask_b32_e64 v252, v252, v236, s[90:91]
	v_cndmask_b32_e64 v253, v253, v237, s[90:91]
	s_add_u32 s34, s34, 0xb000
	s_addc_u32 s35, s35, 0
	s_mov_b64 exec, s[94:95]
	global_load_dwordx4 v[116:119], v189, s[34:35] offset:16
	s_mov_b64 exec, s[90:91]
	global_load_dwordx4 v[112:115], v188, s[34:35] offset:16
	s_mov_b64 exec, -1
	s_waitcnt vmcnt(2)
	v_fma_f32 v208, v62, v230, v226
	v_fma_f32 v209, v63, v231, v227
	v_fma_f32 v210, v64, v232, v228
	v_fma_f32 v211, v65, v233, v229
	v_fmac_f32_dpp v208, v62, v242 row_shr:1 row_mask:0xf bank_mask:0xf
	v_fmac_f32_dpp v209, v63, v243 row_shr:1 row_mask:0xf bank_mask:0xf
	v_fmac_f32_dpp v210, v64, v244 row_shr:1 row_mask:0xf bank_mask:0xf
	v_fmac_f32_dpp v211, v65, v245 row_shr:1 row_mask:0xf bank_mask:0xf
	v_fmac_f32_dpp v208, v62, v246 row_shr:2 row_mask:0xf bank_mask:0xf
	v_fmac_f32_dpp v209, v63, v247 row_shr:2 row_mask:0xf bank_mask:0xf
	v_fmac_f32_dpp v210, v64, v248 row_shr:2 row_mask:0xf bank_mask:0xf
	v_fmac_f32_dpp v211, v65, v249 row_shr:2 row_mask:0xf bank_mask:0xf
	v_fmac_f32_e32 v208, v108, v250
	v_fmac_f32_e32 v209, v109, v251
	v_fmac_f32_e32 v210, v110, v252
	v_fmac_f32_e32 v211, v111, v253
	v_fmac_f32_e32 v208, v104, v204
	v_fmac_f32_e32 v209, v105, v205
	v_fmac_f32_e32 v210, v106, v206
	v_fmac_f32_e32 v211, v107, v207
	v_mul_f32_e32 v86, v208, v208
	v_mul_f32_e32 v87, v209, v209
	v_mul_f32_e32 v92, v210, v210
	v_mul_f32_e32 v93, v211, v211
	v_fmamk_f32 v86, v86, 0xbdd2d3e8, v98
	v_fmamk_f32 v87, v87, 0xbdd2d3e8, v98
	v_fmamk_f32 v92, v92, 0xbdd2d3e8, v98
	v_fmamk_f32 v93, v93, 0xbdd2d3e8, v98
	v_mul_f32_e32 v86, v208, v86
	v_mul_f32_e32 v87, v209, v87
	v_mul_f32_e32 v92, v210, v92
	v_mul_f32_e32 v93, v211, v93
	v_exp_f32_e32 v86, v86
	v_exp_f32_e32 v87, v87
	v_exp_f32_e32 v92, v92
	v_exp_f32_e32 v93, v93
	v_mul_f32_e32 v208, v208, v58
	v_mul_f32_e32 v209, v209, v59
	v_mul_f32_e32 v210, v210, v60
	v_mul_f32_e32 v211, v211, v61
	v_add_f32_e32 v86, 1.0, v86
	v_add_f32_e32 v87, 1.0, v87
	v_add_f32_e32 v92, 1.0, v92
	v_add_f32_e32 v93, 1.0, v93
	v_rcp_f32_e32 v86, v86
	v_rcp_f32_e32 v87, v87
	v_rcp_f32_e32 v92, v92
	v_rcp_f32_e32 v93, v93
	s_nop 0
	v_mul_f32_e32 v208, v208, v86
	v_mul_f32_e32 v209, v209, v87
	v_mul_f32_e32 v210, v210, v92
	v_mul_f32_e32 v211, v211, v93
	v_cvt_pk_bf16_f32 v146, v208, v209
	v_cvt_pk_bf16_f32 v147, v210, v211
	s_mov_b64 exec, s[84:85]
	global_store_dwordx4 v190, v[62:65], s[42:43] offset:16
	s_mov_b64 exec, -1
	global_store_dwordx4 v212, v[144:147], s[80:81]
	s_add_u32 s42, s42, 0xb000
	s_addc_u32 s43, s43, 0
	s_add_u32 s80, s80, 0x16000
	s_addc_u32 s81, s81, 0
	s_add_u32 s34, s34, 0xb000
	s_addc_u32 s35, s35, 0
	s_mov_b64 exec, s[94:95]
	global_load_dwordx4 v[108:111], v189, s[34:35] offset:16
	s_mov_b64 exec, s[90:91]
	global_load_dwordx4 v[104:107], v188, s[34:35] offset:16
	s_mov_b64 exec, -1
	s_waitcnt vmcnt(4)
; __device__ __forceinline__ unsigned cvt_pk_bf16(float lo, float hi) { unsigned r; asm volatile("v_cvt_pk_bf16_f32 %0, %1, %2" : "=v"(r) : "v"(lo), "v"(hi)); return r; }
; __device__ __forceinline__ float frcp(float x) { return __builtin_amdgcn_rcpf(x); }
;     __device__ __forceinline__ void operator()(const f32x4 (&acc)[2][2][4][2], const Unit& u, int wr, int wc, int fr, int fq) const {
;     ...
;                         const int t = fr & 7, bb = (r - 16384) >> 3;
; #pragma unroll
;                         for (int e2 = 0; e2 < 4; ++e2) { p1[e2] = ror1(a[e2]); p2[e2] = ror2(a[e2]); }
;                         if (t < 2) { const f32x4 h1 = *(const f32x4*)(state_conv + ((size_t)bb * 2 + 1) * FF + j0 + 4 * n);
;                             if (t == 0) { p1 = h1; p2 = *(const f32x4*)(state_conv + ((size_t)bb * 2) * FF + j0 + 4 * n); } else p2 = h1; }
;                         if (t >= 6) *(f32x4*)(o_conv_s + ((size_t)bb * 2 + (t - 6)) * FF + j0 + 4 * n) = a;
;                     }
;                     f32x4 hv;
; #pragma unroll
;                     for (int e2 = 0; e2 < 1; ++e2) {
;                         const f32x4 c4 = cb + w0 * p2 + w1 * p1 + w2 * a;
;                         const f32x4 z = c4 * ((c4 * c4) * (-0.10294324f) + (-2.3022082f));
;                         f32x4 den; den[0] = 1.f + __builtin_amdgcn_exp2f(z[0]); den[1] = 1.f + __builtin_amdgcn_exp2f(z[1]); den[2] = 1.f + __builtin_amdgcn_exp2f(z[2]); den[3] = 1.f + __builtin_amdgcn_exp2f(z[3]);
;                         f32x4 rc; rc[0] = frcp(den[0]); rc[1] = frcp(den[1]); rc[2] = frcp(den[2]); rc[3] = frcp(den[3]);
;                         hv = (c4 * rc) * b; }
;                     const u32x2 pkv = (u32x2){cvt_pk_bf16(hv[0], hv[1]), cvt_pk_bf16(hv[2], hv[3])};
;                     if (n == 0) pk0[ai][m] = pkv; else *(u32x4*)(HID + (size_t)r * FF + j0) = (u32x4){pk0[ai][m][0], pk0[ai][m][1], pkv[0], pkv[1]};
	v_fma_f32 v208, v54, v230, v226
	v_fma_f32 v209, v55, v231, v227
	v_fma_f32 v210, v56, v232, v228
	v_fma_f32 v211, v57, v233, v229
	v_fmac_f32_dpp v208, v54, v242 row_shr:1 row_mask:0xf bank_mask:0xf
	v_fmac_f32_dpp v209, v55, v243 row_shr:1 row_mask:0xf bank_mask:0xf
	v_fmac_f32_dpp v210, v56, v244 row_shr:1 row_mask:0xf bank_mask:0xf
	v_fmac_f32_dpp v211, v57, v245 row_shr:1 row_mask:0xf bank_mask:0xf
	v_fmac_f32_dpp v208, v54, v246 row_shr:2 row_mask:0xf bank_mask:0xf
	v_fmac_f32_dpp v209, v55, v247 row_shr:2 row_mask:0xf bank_mask:0xf
	v_fmac_f32_dpp v210, v56, v248 row_shr:2 row_mask:0xf bank_mask:0xf
	v_fmac_f32_dpp v211, v57, v249 row_shr:2 row_mask:0xf bank_mask:0xf
	v_fmac_f32_e32 v208, v116, v250
	v_fmac_f32_e32 v209, v117, v251
	v_fmac_f32_e32 v210, v118, v252
	v_fmac_f32_e32 v211, v119, v253
	v_fmac_f32_e32 v208, v112, v204
	v_fmac_f32_e32 v209, v113, v205
	v_fmac_f32_e32 v210, v114, v206
	v_fmac_f32_e32 v211, v115, v207
	v_mul_f32_e32 v86, v208, v208
	v_mul_f32_e32 v87, v209, v209
	v_mul_f32_e32 v92, v210, v210
	v_mul_f32_e32 v93, v211, v211
	v_fmamk_f32 v86, v86, 0xbdd2d3e8, v98
	v_fmamk_f32 v87, v87, 0xbdd2d3e8, v98
	v_fmamk_f32 v92, v92, 0xbdd2d3e8, v98
	v_fmamk_f32 v93, v93, 0xbdd2d3e8, v98
	v_mul_f32_e32 v86, v208, v86
	v_mul_f32_e32 v87, v209, v87
	v_mul_f32_e32 v92, v210, v92
	v_mul_f32_e32 v93, v211, v93
	v_exp_f32_e32 v86, v86
	v_exp_f32_e32 v87, v87
	v_exp_f32_e32 v92, v92
	v_exp_f32_e32 v93, v93
	v_mul_f32_e32 v208, v208, v50
	v_mul_f32_e32 v209, v209, v51
	v_mul_f32_e32 v210, v210, v52
	v_mul_f32_e32 v211, v211, v53
	v_add_f32_e32 v86, 1.0, v86
	v_add_f32_e32 v87, 1.0, v87
	v_add_f32_e32 v92, 1.0, v92
	v_add_f32_e32 v93, 1.0, v93
	v_rcp_f32_e32 v86, v86
	v_rcp_f32_e32 v87, v87
	v_rcp_f32_e32 v92, v92
	v_rcp_f32_e32 v93, v93
	s_nop 0
	v_mul_f32_e32 v208, v208, v86
	v_mul_f32_e32 v209, v209, v87
	v_mul_f32_e32 v210, v210, v92
	v_mul_f32_e32 v211, v211, v93
	v_cvt_pk_bf16_f32 v138, v208, v209
	v_cvt_pk_bf16_f32 v139, v210, v211
	s_mov_b64 exec, s[84:85]
	global_store_dwordx4 v190, v[54:57], s[42:43] offset:16
	s_mov_b64 exec, -1
	global_store_dwordx4 v212, v[136:139], s[80:81]
	s_add_u32 s42, s42, 0xb000
	s_addc_u32 s43, s43, 0
	s_add_u32 s80, s80, 0x16000
	s_addc_u32 s81, s81, 0
	s_add_u32 s34, s34, 0xb000
	s_addc_u32 s35, s35, 0
	s_mov_b64 exec, s[94:95]
	global_load_dwordx4 v[116:119], v189, s[34:35] offset:16
	s_mov_b64 exec, s[90:91]
	global_load_dwordx4 v[112:115], v188, s[34:35] offset:16
	s_mov_b64 exec, -1
	s_waitcnt vmcnt(4)
	v_fma_f32 v208, v46, v230, v226
	v_fma_f32 v209, v47, v231, v227
	v_fma_f32 v210, v48, v232, v228
	v_fma_f32 v211, v49, v233, v229
	v_fmac_f32_dpp v208, v46, v242 row_shr:1 row_mask:0xf bank_mask:0xf
	v_fmac_f32_dpp v209, v47, v243 row_shr:1 row_mask:0xf bank_mask:0xf
	v_fmac_f32_dpp v210, v48, v244 row_shr:1 row_mask:0xf bank_mask:0xf
	v_fmac_f32_dpp v211, v49, v245 row_shr:1 row_mask:0xf bank_mask:0xf
	v_fmac_f32_dpp v208, v46, v246 row_shr:2 row_mask:0xf bank_mask:0xf
	v_fmac_f32_dpp v209, v47, v247 row_shr:2 row_mask:0xf bank_mask:0xf
	v_fmac_f32_dpp v210, v48, v248 row_shr:2 row_mask:0xf bank_mask:0xf
	v_fmac_f32_dpp v211, v49, v249 row_shr:2 row_mask:0xf bank_mask:0xf
	v_fmac_f32_e32 v208, v108, v250
	v_fmac_f32_e32 v209, v109, v251
	v_fmac_f32_e32 v210, v110, v252
	v_fmac_f32_e32 v211, v111, v253
	v_fmac_f32_e32 v208, v104, v204
	v_fmac_f32_e32 v209, v105, v205
	v_fmac_f32_e32 v210, v106, v206
	v_fmac_f32_e32 v211, v107, v207
	v_mul_f32_e32 v86, v208, v208
	v_mul_f32_e32 v87, v209, v209
	v_mul_f32_e32 v92, v210, v210
	v_mul_f32_e32 v93, v211, v211
	v_fmamk_f32 v86, v86, 0xbdd2d3e8, v98
	v_fmamk_f32 v87, v87, 0xbdd2d3e8, v98
	v_fmamk_f32 v92, v92, 0xbdd2d3e8, v98
	v_fmamk_f32 v93, v93, 0xbdd2d3e8, v98
	v_mul_f32_e32 v86, v208, v86
	v_mul_f32_e32 v87, v209, v87
	v_mul_f32_e32 v92, v210, v92
	v_mul_f32_e32 v93, v211, v93
	v_exp_f32_e32 v86, v86
	v_exp_f32_e32 v87, v87
	v_exp_f32_e32 v92, v92
	v_exp_f32_e32 v93, v93
	v_mul_f32_e32 v208, v208, v42
	v_mul_f32_e32 v209, v209, v43
	v_mul_f32_e32 v210, v210, v44
	v_mul_f32_e32 v211, v211, v45
	v_add_f32_e32 v86, 1.0, v86
	v_add_f32_e32 v87, 1.0, v87
	v_add_f32_e32 v92, 1.0, v92
	v_add_f32_e32 v93, 1.0, v93
	v_rcp_f32_e32 v86, v86
	v_rcp_f32_e32 v87, v87
	v_rcp_f32_e32 v92, v92
	v_rcp_f32_e32 v93, v93
	s_nop 0
	v_mul_f32_e32 v208, v208, v86
	v_mul_f32_e32 v209, v209, v87
	v_mul_f32_e32 v210, v210, v92
	v_mul_f32_e32 v211, v211, v93
	v_cvt_pk_bf16_f32 v130, v208, v209
	v_cvt_pk_bf16_f32 v131, v210, v211
	s_mov_b64 exec, s[84:85]
	global_store_dwordx4 v190, v[46:49], s[42:43] offset:16
	s_mov_b64 exec, -1
	global_store_dwordx4 v212, v[128:131], s[80:81]
	s_add_u32 s42, s42, 0xb000
	s_addc_u32 s43, s43, 0
	s_add_u32 s80, s80, 0x16000
	s_addc_u32 s81, s81, 0
	s_add_u32 s34, s34, 0x37000
	s_addc_u32 s35, s35, 0
	s_mov_b64 exec, s[94:95]
	global_load_dwordx4 v[108:111], v189, s[34:35] offset:16
	s_mov_b64 exec, s[90:91]
	global_load_dwordx4 v[104:107], v188, s[34:35] offset:16
	s_mov_b64 exec, -1
	s_waitcnt vmcnt(4)
; __device__ __forceinline__ unsigned cvt_pk_bf16(float lo, float hi) { unsigned r; asm volatile("v_cvt_pk_bf16_f32 %0, %1, %2" : "=v"(r) : "v"(lo), "v"(hi)); return r; }
; __device__ __forceinline__ float frcp(float x) { return __builtin_amdgcn_rcpf(x); }
;     __device__ __forceinline__ void operator()(const f32x4 (&acc)[2][2][4][2], const Unit& u, int wr, int wc, int fr, int fq) const {
;     ...
;                         const int t = fr & 7, bb = (r - 16384) >> 3;
; #pragma unroll
;                         for (int e2 = 0; e2 < 4; ++e2) { p1[e2] = ror1(a[e2]); p2[e2] = ror2(a[e2]); }
;                         if (t < 2) { const f32x4 h1 = *(const f32x4*)(state_conv + ((size_t)bb * 2 + 1) * FF + j0 + 4 * n);
;                             if (t == 0) { p1 = h1; p2 = *(const f32x4*)(state_conv + ((size_t)bb * 2) * FF + j0 + 4 * n); } else p2 = h1; }
;                         if (t >= 6) *(f32x4*)(o_conv_s + ((size_t)bb * 2 + (t - 6)) * FF + j0 + 4 * n) = a;
;                     }
;                     f32x4 hv;
; #pragma unroll
;                     for (int e2 = 0; e2 < 1; ++e2) {
;                         const f32x4 c4 = cb + w0 * p2 + w1 * p1 + w2 * a;
;                         const f32x4 z = c4 * ((c4 * c4) * (-0.10294324f) + (-2.3022082f));
;                         f32x4 den; den[0] = 1.f + __builtin_amdgcn_exp2f(z[0]); den[1] = 1.f + __builtin_amdgcn_exp2f(z[1]); den[2] = 1.f + __builtin_amdgcn_exp2f(z[2]); den[3] = 1.f + __builtin_amdgcn_exp2f(z[3]);
;                         f32x4 rc; rc[0] = frcp(den[0]); rc[1] = frcp(den[1]); rc[2] = frcp(den[2]); rc[3] = frcp(den[3]);
;                         hv = (c4 * rc) * b; }
;                     const u32x2 pkv = (u32x2){cvt_pk_bf16(hv[0], hv[1]), cvt_pk_bf16(hv[2], hv[3])};
;                     if (n == 0) pk0[ai][m] = pkv; else *(u32x4*)(HID + (size_t)r * FF + j0) = (u32x4){pk0[ai][m][0], pk0[ai][m][1], pkv[0], pkv[1]};
	v_fma_f32 v208, v38, v230, v226
	v_fma_f32 v209, v39, v231, v227
	v_fma_f32 v210, v40, v232, v228
	v_fma_f32 v211, v41, v233, v229
	v_fmac_f32_dpp v208, v38, v242 row_shr:1 row_mask:0xf bank_mask:0xf
	v_fmac_f32_dpp v209, v39, v243 row_shr:1 row_mask:0xf bank_mask:0xf
	v_fmac_f32_dpp v210, v40, v244 row_shr:1 row_mask:0xf bank_mask:0xf
	v_fmac_f32_dpp v211, v41, v245 row_shr:1 row_mask:0xf bank_mask:0xf
	v_fmac_f32_dpp v208, v38, v246 row_shr:2 row_mask:0xf bank_mask:0xf
	v_fmac_f32_dpp v209, v39, v247 row_shr:2 row_mask:0xf bank_mask:0xf
	v_fmac_f32_dpp v210, v40, v248 row_shr:2 row_mask:0xf bank_mask:0xf
	v_fmac_f32_dpp v211, v41, v249 row_shr:2 row_mask:0xf bank_mask:0xf
	v_fmac_f32_e32 v208, v116, v250
	v_fmac_f32_e32 v209, v117, v251
	v_fmac_f32_e32 v210, v118, v252
	v_fmac_f32_e32 v211, v119, v253
	v_fmac_f32_e32 v208, v112, v204
	v_fmac_f32_e32 v209, v113, v205
	v_fmac_f32_e32 v210, v114, v206
	v_fmac_f32_e32 v211, v115, v207
	v_mul_f32_e32 v86, v208, v208
	v_mul_f32_e32 v87, v209, v209
	v_mul_f32_e32 v92, v210, v210
	v_mul_f32_e32 v93, v211, v211
	v_fmamk_f32 v86, v86, 0xbdd2d3e8, v98
	v_fmamk_f32 v87, v87, 0xbdd2d3e8, v98
	v_fmamk_f32 v92, v92, 0xbdd2d3e8, v98
	v_fmamk_f32 v93, v93, 0xbdd2d3e8, v98
	v_mul_f32_e32 v86, v208, v86
	v_mul_f32_e32 v87, v209, v87
	v_mul_f32_e32 v92, v210, v92
	v_mul_f32_e32 v93, v211, v93
	v_exp_f32_e32 v86, v86
	v_exp_f32_e32 v87, v87
	v_exp_f32_e32 v92, v92
	v_exp_f32_e32 v93, v93
	v_mul_f32_e32 v208, v208, v34
	v_mul_f32_e32 v209, v209, v35
	v_mul_f32_e32 v210, v210, v36
	v_mul_f32_e32 v211, v211, v37
	v_add_f32_e32 v86, 1.0, v86
	v_add_f32_e32 v87, 1.0, v87
	v_add_f32_e32 v92, 1.0, v92
	v_add_f32_e32 v93, 1.0, v93
	v_rcp_f32_e32 v86, v86
	v_rcp_f32_e32 v87, v87
	v_rcp_f32_e32 v92, v92
	v_rcp_f32_e32 v93, v93
	s_nop 0
	v_mul_f32_e32 v208, v208, v86
	v_mul_f32_e32 v209, v209, v87
	v_mul_f32_e32 v210, v210, v92
	v_mul_f32_e32 v211, v211, v93
	v_cvt_pk_bf16_f32 v96, v208, v209
	v_cvt_pk_bf16_f32 v97, v210, v211
	s_mov_b64 exec, s[84:85]
	global_store_dwordx4 v190, v[38:41], s[42:43] offset:16
	s_mov_b64 exec, -1
	global_store_dwordx4 v212, v[94:97], s[80:81]
	s_add_u32 s42, s42, 0x37000
	s_addc_u32 s43, s43, 0
	s_add_u32 s80, s80, 0x6e000
	s_addc_u32 s81, s81, 0
	s_add_u32 s34, s34, 0xb000
	s_addc_u32 s35, s35, 0
	s_mov_b64 exec, s[94:95]
	global_load_dwordx4 v[116:119], v189, s[34:35] offset:16
	s_mov_b64 exec, s[90:91]
	global_load_dwordx4 v[112:115], v188, s[34:35] offset:16
	s_mov_b64 exec, -1
	s_waitcnt vmcnt(4)
	v_fma_f32 v208, v30, v230, v226
	v_fma_f32 v209, v31, v231, v227
	v_fma_f32 v210, v32, v232, v228
	v_fma_f32 v211, v33, v233, v229
	v_fmac_f32_dpp v208, v30, v242 row_shr:1 row_mask:0xf bank_mask:0xf
	v_fmac_f32_dpp v209, v31, v243 row_shr:1 row_mask:0xf bank_mask:0xf
	v_fmac_f32_dpp v210, v32, v244 row_shr:1 row_mask:0xf bank_mask:0xf
	v_fmac_f32_dpp v211, v33, v245 row_shr:1 row_mask:0xf bank_mask:0xf
	v_fmac_f32_dpp v208, v30, v246 row_shr:2 row_mask:0xf bank_mask:0xf
	v_fmac_f32_dpp v209, v31, v247 row_shr:2 row_mask:0xf bank_mask:0xf
	v_fmac_f32_dpp v210, v32, v248 row_shr:2 row_mask:0xf bank_mask:0xf
	v_fmac_f32_dpp v211, v33, v249 row_shr:2 row_mask:0xf bank_mask:0xf
	v_fmac_f32_e32 v208, v108, v250
	v_fmac_f32_e32 v209, v109, v251
	v_fmac_f32_e32 v210, v110, v252
	v_fmac_f32_e32 v211, v111, v253
	v_fmac_f32_e32 v208, v104, v204
	v_fmac_f32_e32 v209, v105, v205
	v_fmac_f32_e32 v210, v106, v206
	v_fmac_f32_e32 v211, v107, v207
	v_mul_f32_e32 v86, v208, v208
	v_mul_f32_e32 v87, v209, v209
	v_mul_f32_e32 v92, v210, v210
	v_mul_f32_e32 v93, v211, v211
	v_fmamk_f32 v86, v86, 0xbdd2d3e8, v98
	v_fmamk_f32 v87, v87, 0xbdd2d3e8, v98
	v_fmamk_f32 v92, v92, 0xbdd2d3e8, v98
	v_fmamk_f32 v93, v93, 0xbdd2d3e8, v98
	v_mul_f32_e32 v86, v208, v86
	v_mul_f32_e32 v87, v209, v87
	v_mul_f32_e32 v92, v210, v92
	v_mul_f32_e32 v93, v211, v93
	v_exp_f32_e32 v86, v86
	v_exp_f32_e32 v87, v87
	v_exp_f32_e32 v92, v92
	v_exp_f32_e32 v93, v93
	v_mul_f32_e32 v208, v208, v26
	v_mul_f32_e32 v209, v209, v27
	v_mul_f32_e32 v210, v210, v28
	v_mul_f32_e32 v211, v211, v29
	v_add_f32_e32 v86, 1.0, v86
	v_add_f32_e32 v87, 1.0, v87
	v_add_f32_e32 v92, 1.0, v92
	v_add_f32_e32 v93, 1.0, v93
	v_rcp_f32_e32 v86, v86
	v_rcp_f32_e32 v87, v87
	v_rcp_f32_e32 v92, v92
	v_rcp_f32_e32 v93, v93
	s_nop 0
	v_mul_f32_e32 v208, v208, v86
	v_mul_f32_e32 v209, v209, v87
	v_mul_f32_e32 v210, v210, v92
	v_mul_f32_e32 v211, v211, v93
	v_cvt_pk_bf16_f32 v102, v208, v209
	v_cvt_pk_bf16_f32 v103, v210, v211
	s_mov_b64 exec, s[84:85]
	global_store_dwordx4 v190, v[30:33], s[42:43] offset:16
	s_mov_b64 exec, -1
	global_store_dwordx4 v212, v[100:103], s[80:81]
	s_add_u32 s42, s42, 0xb000
	s_addc_u32 s43, s43, 0
	s_add_u32 s80, s80, 0x16000
	s_addc_u32 s81, s81, 0
	s_add_u32 s34, s34, 0xb000
	s_addc_u32 s35, s35, 0
	s_mov_b64 exec, s[94:95]
	global_load_dwordx4 v[108:111], v189, s[34:35] offset:16
	s_mov_b64 exec, s[90:91]
	global_load_dwordx4 v[104:107], v188, s[34:35] offset:16
	s_mov_b64 exec, -1
	s_waitcnt vmcnt(4)
; __device__ __forceinline__ unsigned cvt_pk_bf16(float lo, float hi) { unsigned r; asm volatile("v_cvt_pk_bf16_f32 %0, %1, %2" : "=v"(r) : "v"(lo), "v"(hi)); return r; }
; __device__ __forceinline__ float frcp(float x) { return __builtin_amdgcn_rcpf(x); }
;     __device__ __forceinline__ void operator()(const f32x4 (&acc)[2][2][4][2], const Unit& u, int wr, int wc, int fr, int fq) const {
;     ...
;                         const int t = fr & 7, bb = (r - 16384) >> 3;
; #pragma unroll
;                         for (int e2 = 0; e2 < 4; ++e2) { p1[e2] = ror1(a[e2]); p2[e2] = ror2(a[e2]); }
;                         if (t < 2) { const f32x4 h1 = *(const f32x4*)(state_conv + ((size_t)bb * 2 + 1) * FF + j0 + 4 * n);
;                             if (t == 0) { p1 = h1; p2 = *(const f32x4*)(state_conv + ((size_t)bb * 2) * FF + j0 + 4 * n); } else p2 = h1; }
;                         if (t >= 6) *(f32x4*)(o_conv_s + ((size_t)bb * 2 + (t - 6)) * FF + j0 + 4 * n) = a;
;                     }
;                     f32x4 hv;
; #pragma unroll
;                     for (int e2 = 0; e2 < 1; ++e2) {
;                         const f32x4 c4 = cb + w0 * p2 + w1 * p1 + w2 * a;
;                         const f32x4 z = c4 * ((c4 * c4) * (-0.10294324f) + (-2.3022082f));
;                         f32x4 den; den[0] = 1.f + __builtin_amdgcn_exp2f(z[0]); den[1] = 1.f + __builtin_amdgcn_exp2f(z[1]); den[2] = 1.f + __builtin_amdgcn_exp2f(z[2]); den[3] = 1.f + __builtin_amdgcn_exp2f(z[3]);
;                         f32x4 rc; rc[0] = frcp(den[0]); rc[1] = frcp(den[1]); rc[2] = frcp(den[2]); rc[3] = frcp(den[3]);
;                         hv = (c4 * rc) * b; }
;                     const u32x2 pkv = (u32x2){cvt_pk_bf16(hv[0], hv[1]), cvt_pk_bf16(hv[2], hv[3])};
;                     if (n == 0) pk0[ai][m] = pkv; else *(u32x4*)(HID + (size_t)r * FF + j0) = (u32x4){pk0[ai][m][0], pk0[ai][m][1], pkv[0], pkv[1]};
	v_fma_f32 v208, v22, v230, v226
	v_fma_f32 v209, v23, v231, v227
	v_fma_f32 v210, v24, v232, v228
	v_fma_f32 v211, v25, v233, v229
	v_fmac_f32_dpp v208, v22, v242 row_shr:1 row_mask:0xf bank_mask:0xf
	v_fmac_f32_dpp v209, v23, v243 row_shr:1 row_mask:0xf bank_mask:0xf
	v_fmac_f32_dpp v210, v24, v244 row_shr:1 row_mask:0xf bank_mask:0xf
	v_fmac_f32_dpp v211, v25, v245 row_shr:1 row_mask:0xf bank_mask:0xf
	v_fmac_f32_dpp v208, v22, v246 row_shr:2 row_mask:0xf bank_mask:0xf
	v_fmac_f32_dpp v209, v23, v247 row_shr:2 row_mask:0xf bank_mask:0xf
	v_fmac_f32_dpp v210, v24, v248 row_shr:2 row_mask:0xf bank_mask:0xf
	v_fmac_f32_dpp v211, v25, v249 row_shr:2 row_mask:0xf bank_mask:0xf
	v_fmac_f32_e32 v208, v116, v250
	v_fmac_f32_e32 v209, v117, v251
	v_fmac_f32_e32 v210, v118, v252
	v_fmac_f32_e32 v211, v119, v253
	v_fmac_f32_e32 v208, v112, v204
	v_fmac_f32_e32 v209, v113, v205
	v_fmac_f32_e32 v210, v114, v206
	v_fmac_f32_e32 v211, v115, v207
	v_mul_f32_e32 v86, v208, v208
	v_mul_f32_e32 v87, v209, v209
	v_mul_f32_e32 v92, v210, v210
	v_mul_f32_e32 v93, v211, v211
	v_fmamk_f32 v86, v86, 0xbdd2d3e8, v98
	v_fmamk_f32 v87, v87, 0xbdd2d3e8, v98
	v_fmamk_f32 v92, v92, 0xbdd2d3e8, v98
	v_fmamk_f32 v93, v93, 0xbdd2d3e8, v98
	v_mul_f32_e32 v86, v208, v86
	v_mul_f32_e32 v87, v209, v87
	v_mul_f32_e32 v92, v210, v92
	v_mul_f32_e32 v93, v211, v93
	v_exp_f32_e32 v86, v86
	v_exp_f32_e32 v87, v87
	v_exp_f32_e32 v92, v92
	v_exp_f32_e32 v93, v93
	v_mul_f32_e32 v208, v208, v18
	v_mul_f32_e32 v209, v209, v19
	v_mul_f32_e32 v210, v210, v20
	v_mul_f32_e32 v211, v211, v21
	v_add_f32_e32 v86, 1.0, v86
	v_add_f32_e32 v87, 1.0, v87
	v_add_f32_e32 v92, 1.0, v92
	v_add_f32_e32 v93, 1.0, v93
	v_rcp_f32_e32 v86, v86
	v_rcp_f32_e32 v87, v87
	v_rcp_f32_e32 v92, v92
	v_rcp_f32_e32 v93, v93
	s_nop 0
	v_mul_f32_e32 v208, v208, v86
	v_mul_f32_e32 v209, v209, v87
	v_mul_f32_e32 v210, v210, v92
	v_mul_f32_e32 v211, v211, v93
	v_cvt_pk_bf16_f32 v84, v208, v209
	v_cvt_pk_bf16_f32 v85, v210, v211
	s_mov_b64 exec, s[84:85]
	global_store_dwordx4 v190, v[22:25], s[42:43] offset:16
	s_mov_b64 exec, -1
	global_store_dwordx4 v212, v[82:85], s[80:81]
	s_add_u32 s42, s42, 0xb000
	s_addc_u32 s43, s43, 0
	s_add_u32 s80, s80, 0x16000
	s_addc_u32 s81, s81, 0
	s_add_u32 s34, s34, 0xb000
	s_addc_u32 s35, s35, 0
	s_mov_b64 exec, s[94:95]
	global_load_dwordx4 v[116:119], v189, s[34:35] offset:16
	s_mov_b64 exec, s[90:91]
	global_load_dwordx4 v[112:115], v188, s[34:35] offset:16
	s_mov_b64 exec, -1
	s_waitcnt vmcnt(4)
	v_fma_f32 v208, v14, v230, v226
	v_fma_f32 v209, v15, v231, v227
	v_fma_f32 v210, v16, v232, v228
	v_fma_f32 v211, v17, v233, v229
	v_fmac_f32_dpp v208, v14, v242 row_shr:1 row_mask:0xf bank_mask:0xf
	v_fmac_f32_dpp v209, v15, v243 row_shr:1 row_mask:0xf bank_mask:0xf
	v_fmac_f32_dpp v210, v16, v244 row_shr:1 row_mask:0xf bank_mask:0xf
	v_fmac_f32_dpp v211, v17, v245 row_shr:1 row_mask:0xf bank_mask:0xf
	v_fmac_f32_dpp v208, v14, v246 row_shr:2 row_mask:0xf bank_mask:0xf
	v_fmac_f32_dpp v209, v15, v247 row_shr:2 row_mask:0xf bank_mask:0xf
	v_fmac_f32_dpp v210, v16, v248 row_shr:2 row_mask:0xf bank_mask:0xf
	v_fmac_f32_dpp v211, v17, v249 row_shr:2 row_mask:0xf bank_mask:0xf
	v_fmac_f32_e32 v208, v108, v250
	v_fmac_f32_e32 v209, v109, v251
	v_fmac_f32_e32 v210, v110, v252
	v_fmac_f32_e32 v211, v111, v253
	v_fmac_f32_e32 v208, v104, v204
	v_fmac_f32_e32 v209, v105, v205
	v_fmac_f32_e32 v210, v106, v206
	v_fmac_f32_e32 v211, v107, v207
	v_mul_f32_e32 v86, v208, v208
	v_mul_f32_e32 v87, v209, v209
	v_mul_f32_e32 v92, v210, v210
	v_mul_f32_e32 v93, v211, v211
	v_fmamk_f32 v86, v86, 0xbdd2d3e8, v98
	v_fmamk_f32 v87, v87, 0xbdd2d3e8, v98
	v_fmamk_f32 v92, v92, 0xbdd2d3e8, v98
	v_fmamk_f32 v93, v93, 0xbdd2d3e8, v98
	v_mul_f32_e32 v86, v208, v86
	v_mul_f32_e32 v87, v209, v87
	v_mul_f32_e32 v92, v210, v92
	v_mul_f32_e32 v93, v211, v93
	v_exp_f32_e32 v86, v86
	v_exp_f32_e32 v87, v87
	v_exp_f32_e32 v92, v92
	v_exp_f32_e32 v93, v93
	v_mul_f32_e32 v208, v208, v10
	v_mul_f32_e32 v209, v209, v11
	v_mul_f32_e32 v210, v210, v12
	v_mul_f32_e32 v211, v211, v13
	v_add_f32_e32 v86, 1.0, v86
	v_add_f32_e32 v87, 1.0, v87
	v_add_f32_e32 v92, 1.0, v92
	v_add_f32_e32 v93, 1.0, v93
	v_rcp_f32_e32 v86, v86
	v_rcp_f32_e32 v87, v87
	v_rcp_f32_e32 v92, v92
	v_rcp_f32_e32 v93, v93
	s_nop 0
	v_mul_f32_e32 v208, v208, v86
	v_mul_f32_e32 v209, v209, v87
	v_mul_f32_e32 v210, v210, v92
	v_mul_f32_e32 v211, v211, v93
	v_cvt_pk_bf16_f32 v72, v208, v209
	v_cvt_pk_bf16_f32 v73, v210, v211
	s_mov_b64 exec, s[84:85]
	global_store_dwordx4 v190, v[14:17], s[42:43] offset:16
	s_mov_b64 exec, -1
	global_store_dwordx4 v212, v[70:73], s[80:81]
	s_add_u32 s42, s42, 0xb000
	s_addc_u32 s43, s43, 0
	s_add_u32 s80, s80, 0x16000
	s_addc_u32 s81, s81, 0
	s_waitcnt vmcnt(2)
	v_fma_f32 v208, v6, v230, v226
	v_fma_f32 v209, v7, v231, v227
	v_fma_f32 v210, v8, v232, v228
	v_fma_f32 v211, v9, v233, v229
	v_fmac_f32_dpp v208, v6, v242 row_shr:1 row_mask:0xf bank_mask:0xf
	v_fmac_f32_dpp v209, v7, v243 row_shr:1 row_mask:0xf bank_mask:0xf
	v_fmac_f32_dpp v210, v8, v244 row_shr:1 row_mask:0xf bank_mask:0xf
	v_fmac_f32_dpp v211, v9, v245 row_shr:1 row_mask:0xf bank_mask:0xf
	v_fmac_f32_dpp v208, v6, v246 row_shr:2 row_mask:0xf bank_mask:0xf
	v_fmac_f32_dpp v209, v7, v247 row_shr:2 row_mask:0xf bank_mask:0xf
	v_fmac_f32_dpp v210, v8, v248 row_shr:2 row_mask:0xf bank_mask:0xf
	v_fmac_f32_dpp v211, v9, v249 row_shr:2 row_mask:0xf bank_mask:0xf
	v_fmac_f32_e32 v208, v116, v250
	v_fmac_f32_e32 v209, v117, v251
	v_fmac_f32_e32 v210, v118, v252
	v_fmac_f32_e32 v211, v119, v253
	v_fmac_f32_e32 v208, v112, v204
	v_fmac_f32_e32 v209, v113, v205
	v_fmac_f32_e32 v210, v114, v206
	v_fmac_f32_e32 v211, v115, v207
	v_mul_f32_e32 v86, v208, v208
	v_mul_f32_e32 v87, v209, v209
	v_mul_f32_e32 v92, v210, v210
	v_mul_f32_e32 v93, v211, v211
	v_fmamk_f32 v86, v86, 0xbdd2d3e8, v98
	v_fmamk_f32 v87, v87, 0xbdd2d3e8, v98
	v_fmamk_f32 v92, v92, 0xbdd2d3e8, v98
	v_fmamk_f32 v93, v93, 0xbdd2d3e8, v98
	v_mul_f32_e32 v86, v208, v86
	v_mul_f32_e32 v87, v209, v87
	v_mul_f32_e32 v92, v210, v92
	v_mul_f32_e32 v93, v211, v93
	v_exp_f32_e32 v86, v86
	v_exp_f32_e32 v87, v87
	v_exp_f32_e32 v92, v92
	v_exp_f32_e32 v93, v93
	v_mul_f32_e32 v208, v208, v2
	v_mul_f32_e32 v209, v209, v3
	v_mul_f32_e32 v210, v210, v4
	v_mul_f32_e32 v211, v211, v5
	v_add_f32_e32 v86, 1.0, v86
	v_add_f32_e32 v87, 1.0, v87
	v_add_f32_e32 v92, 1.0, v92
	v_add_f32_e32 v93, 1.0, v93
	v_rcp_f32_e32 v86, v86
	v_rcp_f32_e32 v87, v87
	v_rcp_f32_e32 v92, v92
	v_rcp_f32_e32 v93, v93
	s_nop 0
	v_mul_f32_e32 v208, v208, v86
	v_mul_f32_e32 v209, v209, v87
	v_mul_f32_e32 v210, v210, v92
	v_mul_f32_e32 v211, v211, v93
	v_cvt_pk_bf16_f32 v68, v208, v209
	v_cvt_pk_bf16_f32 v69, v210, v211
	s_mov_b64 exec, s[84:85]
	global_store_dwordx4 v190, v[6:9], s[42:43] offset:16
	s_mov_b64 exec, -1
	global_store_dwordx4 v212, v[66:69], s[80:81]
	s_branch .Lepi5_done
; #define PG8_BAR __builtin_amdgcn_s_barrier()
; template <class Epi, class Sched, bool ALIGN_EPI = false, bool SP2 = false>
; __device__ __forceinline__ void gemm_phase(PG8_LAS unsigned char* lds, const Gemm g, const Sched& S, const Epi& E) {
;     ...
;         if constexpr (ALIGN_EPI) { if (wr == 0) PG8_BAR; }
;         if constexpr (!Epi::AFTER_DRAIN) { E(acc, cur, wr, wc, fr, fq); S.done(cur); }
;         if (!has_next) break;
; #pragma unroll
;         for (int a = 0; a < 2; ++a)
; #pragma unroll
;             for (int b = 0; b < 2; ++b)
; #pragma unroll
;                 for (int m = 0; m < 4; ++m)
; #pragma unroll
;                     for (int n = 0; n < 2; ++n) acc[a][b][m][n] = (f32x4){0.f, 0.f, 0.f, 0.f};
;         cur = nxt; cA = nA; cB = nB; ++ui;
;         if constexpr (ALIGN_EPI) { if (wr == 1) PG8_BAR; }
;     }
.Lepi5_done:
	v_readlane_b32 s79, v254, 62
	s_andn2_b64 vcc, exec, s[8:9]
	s_mov_b64 s[2:3], -1
	s_cbranch_vccnz .LBB0_881
	s_andn2_b64 vcc, exec, s[12:13]
	s_cbranch_vccnz .LBB0_880
	s_barrier
	s_branch .LBB0_880

; __global__ void __launch_bounds__(NWAVES * 64, 2) mk_fwd(Args args) {
;     extern __shared__ __attribute__((aligned(16))) unsigned char lds[];
	.amdhsa_kernel _Z6mk_fwd4Args
		.amdhsa_group_segment_fixed_size 4096
		.amdhsa_private_segment_fixed_size 0
		.amdhsa_kernarg_size 464
		.amdhsa_user_sgpr_count 2
		.amdhsa_user_sgpr_dispatch_ptr 0
		.amdhsa_user_sgpr_queue_ptr 0
		.amdhsa_user_sgpr_kernarg_segment_ptr 1
		.amdhsa_user_sgpr_dispatch_id 0
		.amdhsa_user_sgpr_kernarg_preload_length 0
		.amdhsa_user_sgpr_kernarg_preload_offset 0
		.amdhsa_user_sgpr_private_segment_size 0
		.amdhsa_uses_dynamic_stack 0
		.amdhsa_enable_private_segment 0
		.amdhsa_system_sgpr_workgroup_id_x 1
		.amdhsa_system_sgpr_workgroup_id_y 0
		.amdhsa_system_sgpr_workgroup_id_z 0
		.amdhsa_system_sgpr_workgroup_info 0
		.amdhsa_system_vgpr_workitem_id 0
		.amdhsa_next_free_vgpr 256
		.amdhsa_next_free_sgpr 98
		.amdhsa_accum_offset 256
		.amdhsa_reserve_vcc 1
		.amdhsa_float_round_mode_32 0
		.amdhsa_float_round_mode_16_64 0
		.amdhsa_float_denorm_mode_32 3
		.amdhsa_float_denorm_mode_16_64 3
		.amdhsa_dx10_clamp 1
		.amdhsa_ieee_mode 1
		.amdhsa_fp16_overflow 0
		.amdhsa_tg_split 0
		.amdhsa_exception_fp_ieee_invalid_op 0
		.amdhsa_exception_fp_denorm_src 0
		.amdhsa_exception_fp_ieee_div_zero 0
		.amdhsa_exception_fp_ieee_overflow 0
		.amdhsa_exception_fp_ieee_underflow 0
		.amdhsa_exception_fp_ieee_inexact 0
		.amdhsa_exception_int_div_zero 0
	.end_amdhsa_kernel

; __global__ void __launch_bounds__(NWAVES * 64, 2) mk_fwd(Args args) {
;     extern __shared__ __attribute__((aligned(16))) unsigned char lds[];
amdhsa.kernels:
  - .agpr_count:     0
    .args:
      - .offset:         0
        .size:           208
        .value_kind:     by_value
      - .offset:         208
        .size:           4
        .value_kind:     hidden_block_count_x
      - .offset:         212
        .size:           4
        .value_kind:     hidden_block_count_y
      - .offset:         216
        .size:           4
        .value_kind:     hidden_block_count_z
      - .offset:         220
        .size:           2
        .value_kind:     hidden_group_size_x
      - .offset:         222
        .size:           2
        .value_kind:     hidden_group_size_y
      - .offset:         224
        .size:           2
        .value_kind:     hidden_group_size_z
      - .offset:         226
        .size:           2
        .value_kind:     hidden_remainder_x
      - .offset:         228
        .size:           2
        .value_kind:     hidden_remainder_y
      - .offset:         230
        .size:           2
        .value_kind:     hidden_remainder_z
      - .offset:         248
        .size:           8
        .value_kind:     hidden_global_offset_x
      - .offset:         256
        .size:           8
        .value_kind:     hidden_global_offset_y
      - .offset:         264
        .size:           8
        .value_kind:     hidden_global_offset_z
      - .offset:         272
        .size:           2
        .value_kind:     hidden_grid_dims
      - .offset:         328
        .size:           4
        .value_kind:     hidden_dynamic_lds_size
    .group_segment_fixed_size: 4096
    .kernarg_segment_align: 8
    .kernarg_segment_size: 464
    .language:       OpenCL C
    .language_version:
      - 2
      - 0
    .max_flat_workgroup_size: 512
    .name:           _Z6mk_fwd4Args
    .private_segment_fixed_size: 0
    .sgpr_count:     104
    .sgpr_spill_count: 90
    .symbol:         _Z6mk_fwd4Args.kd
    .uniform_work_group_size: 1
    .uses_dynamic_stack: false
    .vgpr_count:     256
    .vgpr_spill_count: 0
    .wavefront_size: 64
